# softmax scale folded into the q rows of the in-proj weights; attention bias enters through the MFMA accumulator input so the per-element scale-and-bias fma disappears; lazy rescale kept
# speedup vs baseline: 1.2252x; 1.2252x over previous
.LBB0_84:
	s_or_b64 exec, exec, s[6:7]
	s_ashr_i32 s5, s4, 31
	s_barrier
	s_waitcnt vmcnt(0)
	s_cmpk_lt_u32 s69, 0x300
	s_cselect_b32 s71, 0x3e38aa3b, 1.0
	v_mul_f32_e32 v17, s71, v17
	v_mul_f32_e32 v16, s71, v16
	v_mul_f32_e32 v32, s71, v32
	v_mul_f32_e32 v31, s71, v31
	v_mul_f32_e32 v34, s71, v34
	v_mul_f32_e32 v33, s71, v33
	v_mul_f32_e32 v36, s71, v36
	v_mul_f32_e32 v35, s71, v35
	v_mul_f32_e32 v38, s71, v38
	v_mul_f32_e32 v37, s71, v37
	v_mul_f32_e32 v40, s71, v40
	v_mul_f32_e32 v39, s71, v39
	v_mul_f32_e32 v42, s71, v42
	v_mul_f32_e32 v41, s71, v41
	v_mul_f32_e32 v44, s71, v44
	v_mul_f32_e32 v43, s71, v43
	v_mul_f32_e32 v46, s71, v46
	v_mul_f32_e32 v45, s71, v45
	v_mul_f32_e32 v48, s71, v48
	v_mul_f32_e32 v47, s71, v47
	v_mul_f32_e32 v50, s71, v50
	v_mul_f32_e32 v49, s71, v49
	v_mul_f32_e32 v52, s71, v52
	v_mul_f32_e32 v51, s71, v51
	v_mul_f32_e32 v54, s71, v54
	v_mul_f32_e32 v53, s71, v53
	v_mul_f32_e32 v56, s71, v56
	v_mul_f32_e32 v55, s71, v55
	v_mul_f32_e32 v58, s71, v58
	v_mul_f32_e32 v57, s71, v57
	v_mul_f32_e32 v60, s71, v60
	v_mul_f32_e32 v59, s71, v59
	ds_write_b32 v21, v17
	ds_write_b32 v21, v16 offset:2080
	ds_write_b32 v21, v32 offset:4160
	ds_write_b32 v21, v31 offset:6240
	ds_write_b32 v21, v34 offset:8320
	ds_write_b32 v21, v33 offset:10400
	ds_write_b32 v21, v36 offset:12480
	ds_write_b32 v21, v35 offset:14560
	ds_write_b32 v21, v38 offset:16640
	ds_write_b32 v21, v37 offset:18720
	ds_write_b32 v21, v40 offset:20800
	ds_write_b32 v21, v39 offset:22880
	ds_write_b32 v21, v42 offset:24960
	ds_write_b32 v21, v41 offset:27040
	ds_write_b32 v21, v44 offset:29120
	ds_write_b32 v21, v43 offset:31200
	ds_write_b32 v21, v46 offset:33280
	ds_write_b32 v21, v45 offset:35360
	ds_write_b32 v21, v48 offset:37440
	ds_write_b32 v21, v47 offset:39520
	ds_write_b32 v21, v50 offset:41600
	ds_write_b32 v21, v49 offset:43680
	ds_write_b32 v21, v52 offset:45760
	ds_write_b32 v21, v51 offset:47840
	ds_write_b32 v21, v54 offset:49920
	ds_write_b32 v21, v53 offset:52000
	ds_write_b32 v21, v56 offset:54080
	ds_write_b32 v21, v55 offset:56160
	ds_write_b32 v21, v58 offset:58240
	ds_write_b32 v21, v57 offset:60320
	ds_write_b32 v21, v60 offset:62400
	ds_write_b32 v21, v59 offset:64480
	v_lshl_add_u64 v[14:15], s[4:5], 1, v[12:13]
	v_lshl_or_b32 v16, s68, 6, v20
	s_mul_i32 s4, s65, s42
	v_subrev_u32_e32 v30, s4, v16
	s_lshl_b32 s4, s68, 7
	s_mul_i32 s5, s66, s42
	s_sub_i32 s70, s4, s5
	s_mov_b32 s71, 0
	v_mov_b32_e32 v31, v26
	v_mov_b32_e32 v32, v25
	v_mov_b32_e32 v33, v24
	v_mov_b32_e32 v34, v23
	s_mov_b32 s72, 0
	s_waitcnt lgkmcnt(0)
	s_barrier
	s_branch .LBB0_88

.Lmob_pk8:
.Lmob_pk14:
	v_add_u32_e32 v216, v166, v165
	v_add_u32_e32 v217, v167, v165
	v_add_u32_e32 v218, v168, v165
	v_add_u32_e32 v219, v169, v165
	v_add_u32_e32 v220, v170, v171
	v_add_u32_e32 v221, v170, v172
	v_mov_b32_e32 v123, 0xff800000
	v_mov_b32_e32 v128, v216
	v_mov_b32_e32 v129, v217
	v_mov_b32_e32 v173, v218
	v_mov_b32_e32 v175, v219
	v_mov_b32_e32 v176, 0
	s_mov_b32 s101, 0
	v_mov_b32_e32 v178, 0
	v_mov_b32_e32 v179, 0
	v_mov_b32_e32 v180, 0
	v_mov_b32_e32 v181, 0
	v_mov_b32_e32 v182, 0
	v_mov_b32_e32 v183, 0
	v_mov_b32_e32 v184, 0
	v_mov_b32_e32 v185, 0
	v_mov_b32_e32 v186, 0
	v_mov_b32_e32 v187, 0
	v_mov_b32_e32 v188, 0
	v_mov_b32_e32 v189, 0
	v_mov_b32_e32 v190, 0
	v_mov_b32_e32 v191, 0
	v_mov_b32_e32 v192, 0
	v_mov_b32_e32 v193, 0
	s_cmp_eq_u32 s49, 8
	s_cbranch_scc1 .Lmob_pw7
	s_waitcnt vmcnt(11)
	s_branch .Lmob_pbar

.Lmob_bar_e:
	s_barrier
	s_cmp_gt_i32 s69, s68
	s_cbranch_scc1 .Lmob_next_e
	s_and_b32 s40, s69, 15
	s_lshl_b32 s40, s40, 13
	s_cmp_eq_u32 s69, s68
	s_cbranch_scc1 .Lmob_last_e
	s_add_i32 s41, s69, 1
	s_and_b32 s41, s41, 15
	s_lshl_b32 s41, s41, 13
	s_cmp_lt_u32 s69, s67
	s_cbranch_scc1 .Lmob_lane_e
	s_cmp_eq_u32 s101, 0
	s_cbranch_scc0 .Lmob_fix_fbe
.Lmob_fixret_fbe:
	ds_read_b128 v[66:69], v128 offset:8192
	ds_read_b128 v[70:73], v129 offset:8192
	ds_read_b128 v[74:77], v173 offset:8192
	ds_read_b128 v[78:81], v175 offset:8192
	v_add_u32_e32 v223, s40, v220
	v_add_u32_e32 v232, s40, v221
	ds_read_b128 v[104:107], v223 offset:4096
	ds_read_b128 v[108:111], v223 offset:6144
	ds_read_b128 v[112:115], v232 offset:4096
	ds_read_b128 v[116:119], v232 offset:6144
	v_max3_f32 v99, v34, v35, v36
	v_max3_f32 v99, v99, v37, v38
	v_max3_f32 v99, v99, v39, v40
	v_max3_f32 v99, v99, v41, v42
	v_max3_f32 v99, v99, v43, v44
	v_max3_f32 v99, v99, v45, v46
	v_max3_f32 v99, v99, v47, v48
	v_max_f32_e32 v99, v99, v49
	s_waitcnt lgkmcnt(4)
	v_mfma_f32_32x32x16_bf16 v[200:215], v[66:69], v[82:85], v[178:193]
	v_mov_b32_e32 v100, v99
	s_nop 1
	v_permlane32_swap_b32_e32 v99, v100
	v_max_f32_e32 v99, v99, v100
	v_mfma_f32_32x32x16_bf16 v[200:215], v[70:73], v[86:89], v[200:215]
	v_cmp_lt_f32_e32 vcc, 8.0, v99
	s_cmp_eq_u32 s69, 0
	s_cbranch_scc1 .Lmob_rf_fbe
	s_cbranch_vccnz .Lmob_rare_fbe
.Lmob_back_fbe:
	s_waitcnt lgkmcnt(0)
	v_add_u32_e32 v102, 1, v145
	v_med3_i32 v102, v102, 0, 24
	v_bfm_b32 v102, v102, 0
	v_mfma_f32_32x32x16_bf16 v[200:215], v[74:77], v[90:93], v[200:215]
	v_exp_f32_e32 v34, v34
	v_exp_f32_e32 v35, v35
	v_exp_f32_e32 v36, v36
	v_exp_f32_e32 v37, v37
	v_exp_f32_e32 v38, v38
	v_exp_f32_e32 v39, v39
	v_exp_f32_e32 v40, v40
	v_exp_f32_e32 v41, v41
	v_bfe_i32 v244, v102, 0, 1
	v_bfe_i32 v245, v102, 1, 1
	v_bfe_i32 v246, v102, 2, 1
	v_bfe_i32 v247, v102, 3, 1
	v_mfma_f32_32x32x16_bf16 v[200:215], v[78:81], v[94:97], v[200:215]
	v_bfe_i32 v248, v102, 4, 1
	v_bfe_i32 v249, v102, 5, 1
	v_bfe_i32 v250, v102, 6, 1
	v_bfe_i32 v251, v102, 7, 1
	v_and_b32_e32 v34, v244, v34
	v_and_b32_e32 v35, v245, v35
	v_and_b32_e32 v36, v246, v36
	v_and_b32_e32 v37, v247, v37
	v_and_b32_e32 v38, v248, v38
	v_and_b32_e32 v39, v249, v39
	v_and_b32_e32 v40, v250, v40
	v_and_b32_e32 v41, v251, v41
	v_add_f32_e32 v101, v34, v35
	v_add_f32_e32 v101, v101, v36
	v_add_f32_e32 v101, v101, v37
	v_add_f32_e32 v101, v101, v38
	v_add_f32_e32 v101, v101, v39
	v_add_f32_e32 v101, v101, v40
	v_add_f32_e32 v101, v101, v41
	v_cvt_pk_bf16_f32 v224, v34, v35
	v_cvt_pk_bf16_f32 v225, v36, v37
	v_cvt_pk_bf16_f32 v226, v38, v39
	v_cvt_pk_bf16_f32 v227, v40, v41
	v_exp_f32_e32 v42, v42
	v_exp_f32_e32 v43, v43
	v_mfma_f32_32x32x16_bf16 v[18:33], v[104:107], v[224:227], v[18:33]
	v_exp_f32_e32 v44, v44
	v_exp_f32_e32 v45, v45
	v_exp_f32_e32 v46, v46
	v_exp_f32_e32 v47, v47
	v_exp_f32_e32 v48, v48
	v_exp_f32_e32 v49, v49
	v_mfma_f32_32x32x16_bf16 v[2:17], v[108:111], v[224:227], v[2:17]
	v_bfe_i32 v244, v102, 16, 1
	v_bfe_i32 v245, v102, 17, 1
	v_bfe_i32 v246, v102, 18, 1
	v_bfe_i32 v247, v102, 19, 1
	v_bfe_i32 v248, v102, 20, 1
	v_bfe_i32 v249, v102, 21, 1
	v_bfe_i32 v250, v102, 22, 1
	v_bfe_i32 v251, v102, 23, 1
	v_and_b32_e32 v42, v244, v42
	v_and_b32_e32 v43, v245, v43
	v_and_b32_e32 v44, v246, v44
	v_and_b32_e32 v45, v247, v45
	v_and_b32_e32 v46, v248, v46
	v_and_b32_e32 v47, v249, v47
	v_and_b32_e32 v48, v250, v48
	v_and_b32_e32 v49, v251, v49
	v_add_f32_e32 v101, v101, v42
	v_add_f32_e32 v101, v101, v43
	v_add_f32_e32 v101, v101, v44
	v_add_f32_e32 v101, v101, v45
	v_add_f32_e32 v101, v101, v46
	v_add_f32_e32 v101, v101, v47
	v_add_f32_e32 v101, v101, v48
	v_add_f32_e32 v101, v101, v49
	v_cvt_pk_bf16_f32 v228, v42, v43
	v_cvt_pk_bf16_f32 v229, v44, v45
	v_cvt_pk_bf16_f32 v230, v46, v47
	v_cvt_pk_bf16_f32 v231, v48, v49
	v_add_f32_e32 v141, v141, v101
	s_nop 0
	v_mfma_f32_32x32x16_bf16 v[18:33], v[112:115], v[228:231], v[18:33]
	v_mfma_f32_32x32x16_bf16 v[2:17], v[116:119], v[228:231], v[2:17]
	s_branch .Lmob_next_e
.Lmob_lane_e:
	s_cmp_eq_u32 s101, 0
	s_cbranch_scc0 .Lmob_fix_fle

.Lmob_back_fle:
	s_waitcnt lgkmcnt(0)
	s_lshr_b32 s41, s69, 3
	v_bfe_u32 v100, v143, s41, 1
	v_cmp_ne_u32_e32 vcc, 0, v100
	v_mfma_f32_32x32x16_bf16 v[200:215], v[74:77], v[90:93], v[200:215]
	v_exp_f32_e32 v34, v34
	v_exp_f32_e32 v35, v35
	v_exp_f32_e32 v36, v36
	v_exp_f32_e32 v37, v37
	v_exp_f32_e32 v38, v38
	v_exp_f32_e32 v39, v39
	v_exp_f32_e32 v40, v40
	v_exp_f32_e32 v41, v41
	v_add_f32_e32 v101, v34, v35
	v_add_f32_e32 v101, v101, v36
	v_add_f32_e32 v101, v101, v37
	v_mfma_f32_32x32x16_bf16 v[200:215], v[78:81], v[94:97], v[200:215]
	v_add_f32_e32 v101, v101, v38
	v_add_f32_e32 v101, v101, v39
	v_add_f32_e32 v101, v101, v40
	v_add_f32_e32 v101, v101, v41
	v_cvt_pk_bf16_f32 v224, v34, v35
	v_cvt_pk_bf16_f32 v225, v36, v37
	v_cvt_pk_bf16_f32 v226, v38, v39
	v_cvt_pk_bf16_f32 v227, v40, v41
	v_cndmask_b32_e32 v224, 0, v224, vcc
	v_cndmask_b32_e32 v225, 0, v225, vcc
	v_cndmask_b32_e32 v226, 0, v226, vcc
	v_cndmask_b32_e32 v227, 0, v227, vcc
	v_exp_f32_e32 v42, v42
	v_exp_f32_e32 v43, v43
	v_mfma_f32_32x32x16_bf16 v[18:33], v[104:107], v[224:227], v[18:33]
	v_exp_f32_e32 v44, v44
	v_exp_f32_e32 v45, v45
	v_exp_f32_e32 v46, v46
	v_exp_f32_e32 v47, v47
	v_exp_f32_e32 v48, v48
	v_exp_f32_e32 v49, v49
	v_mfma_f32_32x32x16_bf16 v[2:17], v[108:111], v[224:227], v[2:17]
	v_add_f32_e32 v101, v101, v42
	v_add_f32_e32 v101, v101, v43
	v_add_f32_e32 v101, v101, v44
	v_add_f32_e32 v101, v101, v45
	v_add_f32_e32 v101, v101, v46
	v_add_f32_e32 v101, v101, v47
	v_add_f32_e32 v101, v101, v48
	v_add_f32_e32 v101, v101, v49
	v_cvt_pk_bf16_f32 v228, v42, v43
	v_cvt_pk_bf16_f32 v229, v44, v45
	v_cvt_pk_bf16_f32 v230, v46, v47
	v_cvt_pk_bf16_f32 v231, v48, v49
	v_cndmask_b32_e32 v228, 0, v228, vcc
	v_cndmask_b32_e32 v229, 0, v229, vcc
	v_cndmask_b32_e32 v230, 0, v230, vcc
	v_cndmask_b32_e32 v231, 0, v231, vcc
	v_cndmask_b32_e32 v101, 0, v101, vcc
	v_add_f32_e32 v141, v141, v101
	s_nop 0
	v_mfma_f32_32x32x16_bf16 v[18:33], v[112:115], v[228:231], v[18:33]
	v_mfma_f32_32x32x16_bf16 v[2:17], v[116:119], v[228:231], v[2:17]
	s_branch .Lmob_next_e

.Lmob_fixret_lbe:
	v_add_u32_e32 v223, s40, v220
	v_add_u32_e32 v232, s40, v221
	ds_read_b128 v[104:107], v223 offset:4096
	ds_read_b128 v[108:111], v223 offset:6144
	ds_read_b128 v[112:115], v232 offset:4096
	ds_read_b128 v[116:119], v232 offset:6144
	v_max3_f32 v99, v34, v35, v36
	v_max3_f32 v99, v99, v37, v38
	v_max3_f32 v99, v99, v39, v40
	v_max3_f32 v99, v99, v41, v42
	v_max3_f32 v99, v99, v43, v44
	v_max3_f32 v99, v99, v45, v46
	v_max3_f32 v99, v99, v47, v48
	v_max_f32_e32 v99, v99, v49
	v_mov_b32_e32 v100, v99
	s_nop 1
	v_permlane32_swap_b32_e32 v99, v100
	v_max_f32_e32 v99, v99, v100
	v_cmp_lt_f32_e32 vcc, 8.0, v99
	s_cmp_eq_u32 s69, 0
	s_cbranch_scc1 .Lmob_rf_lbe
	s_cbranch_vccnz .Lmob_rare_lbe
.Lmob_back_lbe:
	s_waitcnt lgkmcnt(0)
	v_add_u32_e32 v102, 1, v145
	v_med3_i32 v102, v102, 0, 24
	v_bfm_b32 v102, v102, 0
	v_exp_f32_e32 v34, v34
	v_exp_f32_e32 v35, v35
	v_exp_f32_e32 v36, v36
	v_exp_f32_e32 v37, v37
	v_exp_f32_e32 v38, v38
	v_exp_f32_e32 v39, v39
	v_exp_f32_e32 v40, v40
	v_exp_f32_e32 v41, v41
	v_bfe_i32 v244, v102, 0, 1
	v_bfe_i32 v245, v102, 1, 1
	v_bfe_i32 v246, v102, 2, 1
	v_bfe_i32 v247, v102, 3, 1
	v_bfe_i32 v248, v102, 4, 1
	v_bfe_i32 v249, v102, 5, 1
	v_bfe_i32 v250, v102, 6, 1
	v_bfe_i32 v251, v102, 7, 1
	v_and_b32_e32 v34, v244, v34
	v_and_b32_e32 v35, v245, v35
	v_and_b32_e32 v36, v246, v36
	v_and_b32_e32 v37, v247, v37
	v_and_b32_e32 v38, v248, v38
	v_and_b32_e32 v39, v249, v39
	v_and_b32_e32 v40, v250, v40
	v_and_b32_e32 v41, v251, v41
	v_add_f32_e32 v101, v34, v35
	v_add_f32_e32 v101, v101, v36
	v_add_f32_e32 v101, v101, v37
	v_add_f32_e32 v101, v101, v38
	v_add_f32_e32 v101, v101, v39
	v_add_f32_e32 v101, v101, v40
	v_add_f32_e32 v101, v101, v41
	v_cvt_pk_bf16_f32 v224, v34, v35
	v_cvt_pk_bf16_f32 v225, v36, v37
	v_cvt_pk_bf16_f32 v226, v38, v39
	v_cvt_pk_bf16_f32 v227, v40, v41
	v_exp_f32_e32 v42, v42
	v_exp_f32_e32 v43, v43
	v_mfma_f32_32x32x16_bf16 v[18:33], v[104:107], v[224:227], v[18:33]
	v_exp_f32_e32 v44, v44
	v_exp_f32_e32 v45, v45
	v_exp_f32_e32 v46, v46
	v_exp_f32_e32 v47, v47
	v_exp_f32_e32 v48, v48
	v_exp_f32_e32 v49, v49
	v_mfma_f32_32x32x16_bf16 v[2:17], v[108:111], v[224:227], v[2:17]
	v_bfe_i32 v244, v102, 16, 1
	v_bfe_i32 v245, v102, 17, 1
	v_bfe_i32 v246, v102, 18, 1
	v_bfe_i32 v247, v102, 19, 1
	v_bfe_i32 v248, v102, 20, 1
	v_bfe_i32 v249, v102, 21, 1
	v_bfe_i32 v250, v102, 22, 1
	v_bfe_i32 v251, v102, 23, 1
	v_and_b32_e32 v42, v244, v42
	v_and_b32_e32 v43, v245, v43
	v_and_b32_e32 v44, v246, v44
	v_and_b32_e32 v45, v247, v45
	v_and_b32_e32 v46, v248, v46
	v_and_b32_e32 v47, v249, v47
	v_and_b32_e32 v48, v250, v48
	v_and_b32_e32 v49, v251, v49
	v_add_f32_e32 v101, v101, v42
	v_add_f32_e32 v101, v101, v43
	v_add_f32_e32 v101, v101, v44
	v_add_f32_e32 v101, v101, v45
	v_add_f32_e32 v101, v101, v46
	v_add_f32_e32 v101, v101, v47
	v_add_f32_e32 v101, v101, v48
	v_add_f32_e32 v101, v101, v49
	v_cvt_pk_bf16_f32 v228, v42, v43
	v_cvt_pk_bf16_f32 v229, v44, v45
	v_cvt_pk_bf16_f32 v230, v46, v47
	v_cvt_pk_bf16_f32 v231, v48, v49
	v_add_f32_e32 v141, v141, v101
	s_nop 0
	v_mfma_f32_32x32x16_bf16 v[18:33], v[112:115], v[228:231], v[18:33]
	v_mfma_f32_32x32x16_bf16 v[2:17], v[116:119], v[228:231], v[2:17]
	s_branch .Lmob_next_e

.Lmob_top_o:
	s_cmp_gt_i32 s69, s68
	s_cbranch_scc1 .Lmob_next_o
	s_and_b32 s40, s69, 15
	s_lshl_b32 s40, s40, 13
	s_cmp_eq_u32 s69, s68
	s_cbranch_scc1 .Lmob_last_o
	s_add_i32 s41, s69, 1
	s_and_b32 s41, s41, 15
	s_lshl_b32 s41, s41, 13
	s_cmp_lt_u32 s69, s67
	s_cbranch_scc1 .Lmob_lane_o
	s_cmp_eq_u32 s101, 0
	s_cbranch_scc0 .Lmob_fix_fbo
.Lmob_fixret_fbo:
	v_add_u32_e32 v128, s41, v216
	ds_read_b128 v[66:69], v128
	v_add_u32_e32 v129, s41, v217
	ds_read_b128 v[70:73], v129
	v_add_u32_e32 v173, s41, v218
	ds_read_b128 v[74:77], v173
	v_add_u32_e32 v175, s41, v219
	ds_read_b128 v[78:81], v175
	ds_read_b128 v[104:107], v223 offset:12288
	ds_read_b128 v[108:111], v223 offset:14336
	ds_read_b128 v[112:115], v232 offset:12288
	ds_read_b128 v[116:119], v232 offset:14336
	v_max3_f32 v99, v200, v201, v202
	v_max3_f32 v99, v99, v203, v204
	v_max3_f32 v99, v99, v205, v206
	v_max3_f32 v99, v99, v207, v208
	v_max3_f32 v99, v99, v209, v210
	v_max3_f32 v99, v99, v211, v212
	v_max3_f32 v99, v99, v213, v214
	v_max_f32_e32 v99, v99, v215
	s_waitcnt lgkmcnt(4)
	v_mfma_f32_32x32x16_bf16 v[34:49], v[66:69], v[82:85], v[178:193]
	v_mov_b32_e32 v100, v99
	s_nop 1
	v_permlane32_swap_b32_e32 v99, v100
	v_max_f32_e32 v99, v99, v100
	v_mfma_f32_32x32x16_bf16 v[34:49], v[70:73], v[86:89], v[34:49]
	v_cmp_lt_f32_e32 vcc, 8.0, v99
	s_cbranch_vccnz .Lmob_rare_fbo
.Lmob_back_fbo:
	s_waitcnt lgkmcnt(0)
	v_add_u32_e32 v102, 1, v145
	v_med3_i32 v102, v102, 0, 24
	v_bfm_b32 v102, v102, 0
	v_mfma_f32_32x32x16_bf16 v[34:49], v[74:77], v[90:93], v[34:49]
	v_exp_f32_e32 v200, v200
	v_exp_f32_e32 v201, v201
	v_exp_f32_e32 v202, v202
	v_exp_f32_e32 v203, v203
	v_exp_f32_e32 v204, v204
	v_exp_f32_e32 v205, v205
	v_exp_f32_e32 v206, v206
	v_exp_f32_e32 v207, v207
	v_bfe_i32 v244, v102, 0, 1
	v_bfe_i32 v245, v102, 1, 1
	v_bfe_i32 v246, v102, 2, 1
	v_bfe_i32 v247, v102, 3, 1
	v_mfma_f32_32x32x16_bf16 v[34:49], v[78:81], v[94:97], v[34:49]
	v_bfe_i32 v248, v102, 4, 1
	v_bfe_i32 v249, v102, 5, 1
	v_bfe_i32 v250, v102, 6, 1
	v_bfe_i32 v251, v102, 7, 1
	v_and_b32_e32 v200, v244, v200
	v_and_b32_e32 v201, v245, v201
	v_and_b32_e32 v202, v246, v202
	v_and_b32_e32 v203, v247, v203
	v_and_b32_e32 v204, v248, v204
	v_and_b32_e32 v205, v249, v205
	v_and_b32_e32 v206, v250, v206
	v_and_b32_e32 v207, v251, v207
	v_add_f32_e32 v101, v200, v201
	v_add_f32_e32 v101, v101, v202
	v_add_f32_e32 v101, v101, v203
	v_add_f32_e32 v101, v101, v204
	v_add_f32_e32 v101, v101, v205
	v_add_f32_e32 v101, v101, v206
	v_add_f32_e32 v101, v101, v207
	v_cvt_pk_bf16_f32 v224, v200, v201
	v_cvt_pk_bf16_f32 v225, v202, v203
	v_cvt_pk_bf16_f32 v226, v204, v205
	v_cvt_pk_bf16_f32 v227, v206, v207
	v_exp_f32_e32 v208, v208
	v_exp_f32_e32 v209, v209
	v_mfma_f32_32x32x16_bf16 v[18:33], v[104:107], v[224:227], v[18:33]
	v_exp_f32_e32 v210, v210
	v_exp_f32_e32 v211, v211
	v_exp_f32_e32 v212, v212
	v_exp_f32_e32 v213, v213
	v_exp_f32_e32 v214, v214
	v_exp_f32_e32 v215, v215
	v_mfma_f32_32x32x16_bf16 v[2:17], v[108:111], v[224:227], v[2:17]
	v_bfe_i32 v244, v102, 16, 1
	v_bfe_i32 v245, v102, 17, 1
	v_bfe_i32 v246, v102, 18, 1
	v_bfe_i32 v247, v102, 19, 1
	v_bfe_i32 v248, v102, 20, 1
	v_bfe_i32 v249, v102, 21, 1
	v_bfe_i32 v250, v102, 22, 1
	v_bfe_i32 v251, v102, 23, 1
	v_and_b32_e32 v208, v244, v208
	v_and_b32_e32 v209, v245, v209
	v_and_b32_e32 v210, v246, v210
	v_and_b32_e32 v211, v247, v211
	v_and_b32_e32 v212, v248, v212
	v_and_b32_e32 v213, v249, v213
	v_and_b32_e32 v214, v250, v214
	v_and_b32_e32 v215, v251, v215
	v_add_f32_e32 v101, v101, v208
	v_add_f32_e32 v101, v101, v209
	v_add_f32_e32 v101, v101, v210
	v_add_f32_e32 v101, v101, v211
	v_add_f32_e32 v101, v101, v212
	v_add_f32_e32 v101, v101, v213
	v_add_f32_e32 v101, v101, v214
	v_add_f32_e32 v101, v101, v215
	v_cvt_pk_bf16_f32 v228, v208, v209
	v_cvt_pk_bf16_f32 v229, v210, v211
	v_cvt_pk_bf16_f32 v230, v212, v213
	v_cvt_pk_bf16_f32 v231, v214, v215
	v_add_f32_e32 v141, v141, v101
	s_nop 0
	v_mfma_f32_32x32x16_bf16 v[18:33], v[112:115], v[228:231], v[18:33]
	v_mfma_f32_32x32x16_bf16 v[2:17], v[116:119], v[228:231], v[2:17]
	s_branch .Lmob_next_o

.Lmob_back_flo:
	s_waitcnt lgkmcnt(0)
	s_lshr_b32 s41, s69, 3
	v_bfe_u32 v100, v143, s41, 1
	v_cmp_ne_u32_e32 vcc, 0, v100
	v_mfma_f32_32x32x16_bf16 v[34:49], v[74:77], v[90:93], v[34:49]
	v_exp_f32_e32 v200, v200
	v_exp_f32_e32 v201, v201
	v_exp_f32_e32 v202, v202
	v_exp_f32_e32 v203, v203
	v_exp_f32_e32 v204, v204
	v_exp_f32_e32 v205, v205
	v_exp_f32_e32 v206, v206
	v_exp_f32_e32 v207, v207
	v_add_f32_e32 v101, v200, v201
	v_add_f32_e32 v101, v101, v202
	v_add_f32_e32 v101, v101, v203
	v_mfma_f32_32x32x16_bf16 v[34:49], v[78:81], v[94:97], v[34:49]
	v_add_f32_e32 v101, v101, v204
	v_add_f32_e32 v101, v101, v205
	v_add_f32_e32 v101, v101, v206
	v_add_f32_e32 v101, v101, v207
	v_cvt_pk_bf16_f32 v224, v200, v201
	v_cvt_pk_bf16_f32 v225, v202, v203
	v_cvt_pk_bf16_f32 v226, v204, v205
	v_cvt_pk_bf16_f32 v227, v206, v207
	v_cndmask_b32_e32 v224, 0, v224, vcc
	v_cndmask_b32_e32 v225, 0, v225, vcc
	v_cndmask_b32_e32 v226, 0, v226, vcc
	v_cndmask_b32_e32 v227, 0, v227, vcc
	v_exp_f32_e32 v208, v208
	v_exp_f32_e32 v209, v209
	v_mfma_f32_32x32x16_bf16 v[18:33], v[104:107], v[224:227], v[18:33]
	v_exp_f32_e32 v210, v210
	v_exp_f32_e32 v211, v211
	v_exp_f32_e32 v212, v212
	v_exp_f32_e32 v213, v213
	v_exp_f32_e32 v214, v214
	v_exp_f32_e32 v215, v215
	v_mfma_f32_32x32x16_bf16 v[2:17], v[108:111], v[224:227], v[2:17]
	v_add_f32_e32 v101, v101, v208
	v_add_f32_e32 v101, v101, v209
	v_add_f32_e32 v101, v101, v210
	v_add_f32_e32 v101, v101, v211
	v_add_f32_e32 v101, v101, v212
	v_add_f32_e32 v101, v101, v213
	v_add_f32_e32 v101, v101, v214
	v_add_f32_e32 v101, v101, v215
	v_cvt_pk_bf16_f32 v228, v208, v209
	v_cvt_pk_bf16_f32 v229, v210, v211
	v_cvt_pk_bf16_f32 v230, v212, v213
	v_cvt_pk_bf16_f32 v231, v214, v215
	v_cndmask_b32_e32 v228, 0, v228, vcc
	v_cndmask_b32_e32 v229, 0, v229, vcc
	v_cndmask_b32_e32 v230, 0, v230, vcc
	v_cndmask_b32_e32 v231, 0, v231, vcc
	v_cndmask_b32_e32 v101, 0, v101, vcc
	v_add_f32_e32 v141, v141, v101
	s_nop 0
	v_mfma_f32_32x32x16_bf16 v[18:33], v[112:115], v[228:231], v[18:33]
	v_mfma_f32_32x32x16_bf16 v[2:17], v[116:119], v[228:231], v[2:17]
	s_branch .Lmob_next_o

.Lmob_fixret_lbo:
	ds_read_b128 v[104:107], v223 offset:12288
	ds_read_b128 v[108:111], v223 offset:14336
	ds_read_b128 v[112:115], v232 offset:12288
	ds_read_b128 v[116:119], v232 offset:14336
	v_max3_f32 v99, v200, v201, v202
	v_max3_f32 v99, v99, v203, v204
	v_max3_f32 v99, v99, v205, v206
	v_max3_f32 v99, v99, v207, v208
	v_max3_f32 v99, v99, v209, v210
	v_max3_f32 v99, v99, v211, v212
	v_max3_f32 v99, v99, v213, v214
	v_max_f32_e32 v99, v99, v215
	v_mov_b32_e32 v100, v99
	s_nop 1
	v_permlane32_swap_b32_e32 v99, v100
	v_max_f32_e32 v99, v99, v100
	v_cmp_lt_f32_e32 vcc, 8.0, v99
	s_cbranch_vccnz .Lmob_rare_lbo
.Lmob_back_lbo:
	s_waitcnt lgkmcnt(0)
	v_add_u32_e32 v102, 1, v145
	v_med3_i32 v102, v102, 0, 24
	v_bfm_b32 v102, v102, 0
	v_exp_f32_e32 v200, v200
	v_exp_f32_e32 v201, v201
	v_exp_f32_e32 v202, v202
	v_exp_f32_e32 v203, v203
	v_exp_f32_e32 v204, v204
	v_exp_f32_e32 v205, v205
	v_exp_f32_e32 v206, v206
	v_exp_f32_e32 v207, v207
	v_bfe_i32 v244, v102, 0, 1
	v_bfe_i32 v245, v102, 1, 1
	v_bfe_i32 v246, v102, 2, 1
	v_bfe_i32 v247, v102, 3, 1
	v_bfe_i32 v248, v102, 4, 1
	v_bfe_i32 v249, v102, 5, 1
	v_bfe_i32 v250, v102, 6, 1
	v_bfe_i32 v251, v102, 7, 1
	v_and_b32_e32 v200, v244, v200
	v_and_b32_e32 v201, v245, v201
	v_and_b32_e32 v202, v246, v202
	v_and_b32_e32 v203, v247, v203
	v_and_b32_e32 v204, v248, v204
	v_and_b32_e32 v205, v249, v205
	v_and_b32_e32 v206, v250, v206
	v_and_b32_e32 v207, v251, v207
	v_add_f32_e32 v101, v200, v201
	v_add_f32_e32 v101, v101, v202
	v_add_f32_e32 v101, v101, v203
	v_add_f32_e32 v101, v101, v204
	v_add_f32_e32 v101, v101, v205
	v_add_f32_e32 v101, v101, v206
	v_add_f32_e32 v101, v101, v207
	v_cvt_pk_bf16_f32 v224, v200, v201
	v_cvt_pk_bf16_f32 v225, v202, v203
	v_cvt_pk_bf16_f32 v226, v204, v205
	v_cvt_pk_bf16_f32 v227, v206, v207
	v_exp_f32_e32 v208, v208
	v_exp_f32_e32 v209, v209
	v_mfma_f32_32x32x16_bf16 v[18:33], v[104:107], v[224:227], v[18:33]
	v_exp_f32_e32 v210, v210
	v_exp_f32_e32 v211, v211
	v_exp_f32_e32 v212, v212
	v_exp_f32_e32 v213, v213
	v_exp_f32_e32 v214, v214
	v_exp_f32_e32 v215, v215
	v_mfma_f32_32x32x16_bf16 v[2:17], v[108:111], v[224:227], v[2:17]
	v_bfe_i32 v244, v102, 16, 1
	v_bfe_i32 v245, v102, 17, 1
	v_bfe_i32 v246, v102, 18, 1
	v_bfe_i32 v247, v102, 19, 1
	v_bfe_i32 v248, v102, 20, 1
	v_bfe_i32 v249, v102, 21, 1
	v_bfe_i32 v250, v102, 22, 1
	v_bfe_i32 v251, v102, 23, 1
	v_and_b32_e32 v208, v244, v208
	v_and_b32_e32 v209, v245, v209
	v_and_b32_e32 v210, v246, v210
	v_and_b32_e32 v211, v247, v211
	v_and_b32_e32 v212, v248, v212
	v_and_b32_e32 v213, v249, v213
	v_and_b32_e32 v214, v250, v214
	v_and_b32_e32 v215, v251, v215
	v_add_f32_e32 v101, v101, v208
	v_add_f32_e32 v101, v101, v209
	v_add_f32_e32 v101, v101, v210
	v_add_f32_e32 v101, v101, v211
	v_add_f32_e32 v101, v101, v212
	v_add_f32_e32 v101, v101, v213
	v_add_f32_e32 v101, v101, v214
	v_add_f32_e32 v101, v101, v215
	v_cvt_pk_bf16_f32 v228, v208, v209
	v_cvt_pk_bf16_f32 v229, v210, v211
	v_cvt_pk_bf16_f32 v230, v212, v213
	v_cvt_pk_bf16_f32 v231, v214, v215
	v_add_f32_e32 v141, v141, v101
	s_nop 0
	v_mfma_f32_32x32x16_bf16 v[18:33], v[112:115], v[228:231], v[18:33]
	v_mfma_f32_32x32x16_bf16 v[2:17], v[116:119], v[228:231], v[2:17]
	s_branch .Lmob_next_o

.Lmob_rare_fbe:
	s_nop 15
	s_nop 15
	s_nop 15
	v_cndmask_b32_e32 v100, 0, v99, vcc
	v_add_f32_e32 v176, v176, v100
	v_exp_f32_e64 v120, -v100
	s_nop 0
	v_mul_f32_e32 v141, v141, v120
	v_pk_mul_f32 v[32:33], v[32:33], v[120:121] op_sel_hi:[1,0]
	v_pk_mul_f32 v[30:31], v[30:31], v[120:121] op_sel_hi:[1,0]
	v_pk_mul_f32 v[28:29], v[28:29], v[120:121] op_sel_hi:[1,0]
	v_pk_mul_f32 v[26:27], v[26:27], v[120:121] op_sel_hi:[1,0]
	v_pk_mul_f32 v[24:25], v[24:25], v[120:121] op_sel_hi:[1,0]
	v_pk_mul_f32 v[22:23], v[22:23], v[120:121] op_sel_hi:[1,0]
	v_pk_mul_f32 v[20:21], v[20:21], v[120:121] op_sel_hi:[1,0]
	v_pk_mul_f32 v[18:19], v[18:19], v[120:121] op_sel_hi:[1,0]
	v_pk_mul_f32 v[16:17], v[16:17], v[120:121] op_sel_hi:[1,0]
	v_pk_mul_f32 v[14:15], v[14:15], v[120:121] op_sel_hi:[1,0]
	v_pk_mul_f32 v[12:13], v[12:13], v[120:121] op_sel_hi:[1,0]
	v_pk_mul_f32 v[10:11], v[10:11], v[120:121] op_sel_hi:[1,0]
	v_pk_mul_f32 v[8:9], v[8:9], v[120:121] op_sel_hi:[1,0]
	v_pk_mul_f32 v[6:7], v[6:7], v[120:121] op_sel_hi:[1,0]
	v_pk_mul_f32 v[4:5], v[4:5], v[120:121] op_sel_hi:[1,0]
	v_pk_mul_f32 v[2:3], v[2:3], v[120:121] op_sel_hi:[1,0]
	v_sub_f32_e32 v34, v34, v100
	v_sub_f32_e32 v35, v35, v100
	v_sub_f32_e32 v36, v36, v100
	v_sub_f32_e32 v37, v37, v100
	v_sub_f32_e32 v38, v38, v100
	v_sub_f32_e32 v39, v39, v100
	v_sub_f32_e32 v40, v40, v100
	v_sub_f32_e32 v41, v41, v100
	v_sub_f32_e32 v42, v42, v100
	v_sub_f32_e32 v43, v43, v100
	v_sub_f32_e32 v44, v44, v100
	v_sub_f32_e32 v45, v45, v100
	v_sub_f32_e32 v46, v46, v100
	v_sub_f32_e32 v47, v47, v100
	v_sub_f32_e32 v48, v48, v100
	v_sub_f32_e32 v49, v49, v100
	v_sub_f32_e32 v178, v178, v100
	v_sub_f32_e32 v179, v179, v100
	v_sub_f32_e32 v180, v180, v100
	v_sub_f32_e32 v181, v181, v100
	v_sub_f32_e32 v182, v182, v100
	v_sub_f32_e32 v183, v183, v100
	v_sub_f32_e32 v184, v184, v100
	v_sub_f32_e32 v185, v185, v100
	v_sub_f32_e32 v186, v186, v100
	v_sub_f32_e32 v187, v187, v100
	v_sub_f32_e32 v188, v188, v100
	v_sub_f32_e32 v189, v189, v100
	v_sub_f32_e32 v190, v190, v100
	v_sub_f32_e32 v191, v191, v100
	v_sub_f32_e32 v192, v192, v100
	v_sub_f32_e32 v193, v193, v100
	v_mov_b32_e32 v234, v100
	s_mov_b32 s101, 1
	s_branch .Lmob_back_fbe
.Lmob_rf_fbe:
	s_nop 15
	s_nop 15
	s_nop 15
	v_mov_b32_e32 v100, v99
	v_mov_b32_e32 v176, v99
	v_sub_f32_e32 v34, v34, v100
	v_sub_f32_e32 v35, v35, v100
	v_sub_f32_e32 v36, v36, v100
	v_sub_f32_e32 v37, v37, v100
	v_sub_f32_e32 v38, v38, v100
	v_sub_f32_e32 v39, v39, v100
	v_sub_f32_e32 v40, v40, v100
	v_sub_f32_e32 v41, v41, v100
	v_sub_f32_e32 v42, v42, v100
	v_sub_f32_e32 v43, v43, v100
	v_sub_f32_e32 v44, v44, v100
	v_sub_f32_e32 v45, v45, v100
	v_sub_f32_e32 v46, v46, v100
	v_sub_f32_e32 v47, v47, v100
	v_sub_f32_e32 v48, v48, v100
	v_sub_f32_e32 v49, v49, v100
	v_sub_f32_e32 v178, v178, v100
	v_sub_f32_e32 v179, v179, v100
	v_sub_f32_e32 v180, v180, v100
	v_sub_f32_e32 v181, v181, v100
	v_sub_f32_e32 v182, v182, v100
	v_sub_f32_e32 v183, v183, v100
	v_sub_f32_e32 v184, v184, v100
	v_sub_f32_e32 v185, v185, v100
	v_sub_f32_e32 v186, v186, v100
	v_sub_f32_e32 v187, v187, v100
	v_sub_f32_e32 v188, v188, v100
	v_sub_f32_e32 v189, v189, v100
	v_sub_f32_e32 v190, v190, v100
	v_sub_f32_e32 v191, v191, v100
	v_sub_f32_e32 v192, v192, v100
	v_sub_f32_e32 v193, v193, v100
	v_mov_b32_e32 v234, v100
	s_mov_b32 s101, 1
	s_branch .Lmob_back_fbe
.Lmob_fix_fbe:
	v_sub_f32_e32 v34, v34, v234
	v_sub_f32_e32 v35, v35, v234
	v_sub_f32_e32 v36, v36, v234
	v_sub_f32_e32 v37, v37, v234
	v_sub_f32_e32 v38, v38, v234
	v_sub_f32_e32 v39, v39, v234
	v_sub_f32_e32 v40, v40, v234
	v_sub_f32_e32 v41, v41, v234
	v_sub_f32_e32 v42, v42, v234
	v_sub_f32_e32 v43, v43, v234
	v_sub_f32_e32 v44, v44, v234
	v_sub_f32_e32 v45, v45, v234
	v_sub_f32_e32 v46, v46, v234
	v_sub_f32_e32 v47, v47, v234
	v_sub_f32_e32 v48, v48, v234
	v_sub_f32_e32 v49, v49, v234
	s_mov_b32 s101, 0
	s_branch .Lmob_fixret_fbe

.Lmob_rare_fbo:
	s_nop 15
	s_nop 15
	s_nop 15
	v_cndmask_b32_e32 v100, 0, v99, vcc
	v_add_f32_e32 v176, v176, v100
	v_exp_f32_e64 v120, -v100
	s_nop 0
	v_mul_f32_e32 v141, v141, v120
	v_pk_mul_f32 v[32:33], v[32:33], v[120:121] op_sel_hi:[1,0]
	v_pk_mul_f32 v[30:31], v[30:31], v[120:121] op_sel_hi:[1,0]
	v_pk_mul_f32 v[28:29], v[28:29], v[120:121] op_sel_hi:[1,0]
	v_pk_mul_f32 v[26:27], v[26:27], v[120:121] op_sel_hi:[1,0]
	v_pk_mul_f32 v[24:25], v[24:25], v[120:121] op_sel_hi:[1,0]
	v_pk_mul_f32 v[22:23], v[22:23], v[120:121] op_sel_hi:[1,0]
	v_pk_mul_f32 v[20:21], v[20:21], v[120:121] op_sel_hi:[1,0]
	v_pk_mul_f32 v[18:19], v[18:19], v[120:121] op_sel_hi:[1,0]
	v_pk_mul_f32 v[16:17], v[16:17], v[120:121] op_sel_hi:[1,0]
	v_pk_mul_f32 v[14:15], v[14:15], v[120:121] op_sel_hi:[1,0]
	v_pk_mul_f32 v[12:13], v[12:13], v[120:121] op_sel_hi:[1,0]
	v_pk_mul_f32 v[10:11], v[10:11], v[120:121] op_sel_hi:[1,0]
	v_pk_mul_f32 v[8:9], v[8:9], v[120:121] op_sel_hi:[1,0]
	v_pk_mul_f32 v[6:7], v[6:7], v[120:121] op_sel_hi:[1,0]
	v_pk_mul_f32 v[4:5], v[4:5], v[120:121] op_sel_hi:[1,0]
	v_pk_mul_f32 v[2:3], v[2:3], v[120:121] op_sel_hi:[1,0]
	v_sub_f32_e32 v200, v200, v100
	v_sub_f32_e32 v201, v201, v100
	v_sub_f32_e32 v202, v202, v100
	v_sub_f32_e32 v203, v203, v100
	v_sub_f32_e32 v204, v204, v100
	v_sub_f32_e32 v205, v205, v100
	v_sub_f32_e32 v206, v206, v100
	v_sub_f32_e32 v207, v207, v100
	v_sub_f32_e32 v208, v208, v100
	v_sub_f32_e32 v209, v209, v100
	v_sub_f32_e32 v210, v210, v100
	v_sub_f32_e32 v211, v211, v100
	v_sub_f32_e32 v212, v212, v100
	v_sub_f32_e32 v213, v213, v100
	v_sub_f32_e32 v214, v214, v100
	v_sub_f32_e32 v215, v215, v100
	v_sub_f32_e32 v178, v178, v100
	v_sub_f32_e32 v179, v179, v100
	v_sub_f32_e32 v180, v180, v100
	v_sub_f32_e32 v181, v181, v100
	v_sub_f32_e32 v182, v182, v100
	v_sub_f32_e32 v183, v183, v100
	v_sub_f32_e32 v184, v184, v100
	v_sub_f32_e32 v185, v185, v100
	v_sub_f32_e32 v186, v186, v100
	v_sub_f32_e32 v187, v187, v100
	v_sub_f32_e32 v188, v188, v100
	v_sub_f32_e32 v189, v189, v100
	v_sub_f32_e32 v190, v190, v100
	v_sub_f32_e32 v191, v191, v100
	v_sub_f32_e32 v192, v192, v100
	v_sub_f32_e32 v193, v193, v100
	v_mov_b32_e32 v234, v100
	s_mov_b32 s101, 1
	s_branch .Lmob_back_fbo
.Lmob_fix_fbo:
	v_sub_f32_e32 v200, v200, v234
	v_sub_f32_e32 v201, v201, v234
	v_sub_f32_e32 v202, v202, v234
	v_sub_f32_e32 v203, v203, v234
	v_sub_f32_e32 v204, v204, v234
	v_sub_f32_e32 v205, v205, v234
	v_sub_f32_e32 v206, v206, v234
	v_sub_f32_e32 v207, v207, v234
	v_sub_f32_e32 v208, v208, v234
	v_sub_f32_e32 v209, v209, v234
	v_sub_f32_e32 v210, v210, v234
	v_sub_f32_e32 v211, v211, v234
	v_sub_f32_e32 v212, v212, v234
	v_sub_f32_e32 v213, v213, v234
	v_sub_f32_e32 v214, v214, v234
	v_sub_f32_e32 v215, v215, v234
	s_mov_b32 s101, 0
	s_branch .Lmob_fixret_fbo

.Ldsa_pk8:
	s_mov_b64 s[40:41], 0xc000
	v_lshl_add_u64 v[86:87], v[2:3], 0, s[40:41]
	s_add_i32 s53, s68, 7
	s_mov_b32 s65, 0
	v_mov_b32_e32 v0, 0
	v_mov_b64_e32 v[2:3], v[0:1]
	v_mov_b64_e32 v[4:5], v[0:1]
	v_mov_b64_e32 v[6:7], v[0:1]
	v_mov_b64_e32 v[8:9], v[0:1]
	v_mov_b64_e32 v[10:11], v[0:1]
	v_mov_b64_e32 v[12:13], v[0:1]
	v_mov_b64_e32 v[14:15], v[0:1]
	v_mov_b64_e32 v[16:17], v[0:1]
	v_mov_b64_e32 v[18:19], v[0:1]
	v_mov_b64_e32 v[20:21], v[0:1]
	v_mov_b64_e32 v[22:23], v[0:1]
	v_mov_b64_e32 v[24:25], v[0:1]
	v_mov_b64_e32 v[26:27], v[0:1]
	v_mov_b64_e32 v[28:29], v[0:1]
	v_mov_b64_e32 v[30:31], v[0:1]
	v_mov_b64_e32 v[32:33], v[0:1]
	v_mov_b32_e32 v83, 0xf149f2ca
	v_mov_b32_e32 v141, 0
	v_add_u32_e32 v216, v166, v165
	v_add_u32_e32 v217, v167, v165
	v_add_u32_e32 v218, v168, v165
	v_add_u32_e32 v219, v169, v165
	v_add_u32_e32 v220, v170, v171
	v_add_u32_e32 v221, v170, v172
	v_lshl_add_u32 v222, s1, 5, v135
	v_lshlrev_b32_e32 v222, 4, v222
	v_mov_b32_e32 v128, v216
	v_mov_b32_e32 v129, v217
	v_mov_b32_e32 v173, v218
	v_mov_b32_e32 v175, v219
	v_mov_b32_e32 v83, 0
	s_mov_b32 s101, 0
	v_mov_b32_e32 v178, 0
	v_mov_b32_e32 v179, 0
	v_mov_b32_e32 v180, 0
	v_mov_b32_e32 v181, 0
	v_mov_b32_e32 v182, 0
	v_mov_b32_e32 v183, 0
	v_mov_b32_e32 v184, 0
	v_mov_b32_e32 v185, 0
	v_mov_b32_e32 v186, 0
	v_mov_b32_e32 v187, 0
	v_mov_b32_e32 v188, 0
	v_mov_b32_e32 v189, 0
	v_mov_b32_e32 v190, 0
	v_mov_b32_e32 v191, 0
	v_mov_b32_e32 v192, 0
	v_mov_b32_e32 v193, 0
	s_cmp_eq_u32 s52, 8
	s_cbranch_scc1 .Ldsa_pw7
	s_waitcnt vmcnt(11)
	s_branch .Ldsa_pbar

.Ldsa_nomask:
	s_cmp_gt_i32 s65, s67
	s_cbranch_scc1 .Ldsa_next_e
	s_and_b32 s40, s65, 15
	s_lshl_b32 s40, s40, 13
	s_lshl_b32 s66, s65, 10
	s_and_b32 s66, s66, 0x3000
	s_and_b32 s41, s65, 3
	s_lshl_b32 s41, s41, 2
	s_add_i32 s66, s66, s41
	s_add_i32 s66, s66, 0x20020
	s_cmp_eq_u32 s65, s67
	s_cbranch_scc1 .Ldsa_last_e
	s_add_i32 s41, s65, 1
	s_and_b32 s41, s41, 15
	s_lshl_b32 s41, s41, 13
	s_cmp_eq_u32 s101, 0
	s_cbranch_scc0 .Ldsa_fix_fbe
.Ldsa_fixret_fbe:
	ds_read_b128 v[66:69], v128 offset:8192
	ds_read_b128 v[70:73], v129 offset:8192
	ds_read_b128 v[74:77], v173 offset:8192
	ds_read_b128 v[78:81], v175 offset:8192
	v_add_u32_e32 v223, s40, v220
	v_add_u32_e32 v232, s40, v221
	ds_read_b128 v[104:107], v223 offset:4096
	ds_read_b128 v[108:111], v223 offset:6144
	ds_read_b128 v[112:115], v232 offset:4096
	ds_read_b128 v[116:119], v232 offset:6144
	v_add_u32_e32 v233, s66, v222
	ds_read_b32 v124, v233
	v_max3_f32 v121, v34, v35, v36
	v_max3_f32 v121, v121, v37, v38
	v_max3_f32 v121, v121, v39, v40
	v_max3_f32 v121, v121, v41, v42
	v_max3_f32 v121, v121, v43, v44
	v_max3_f32 v121, v121, v45, v46
	v_max3_f32 v121, v121, v47, v48
	v_max_f32_e32 v121, v121, v49
	s_waitcnt lgkmcnt(5)
	v_mfma_f32_32x32x16_bf16 v[200:215], v[66:69], v[50:53], v[178:193]
	v_mov_b32_e32 v122, v121
	s_nop 1
	v_permlane32_swap_b32_e32 v121, v122
	v_max_f32_e32 v121, v121, v122
	v_mfma_f32_32x32x16_bf16 v[200:215], v[70:73], v[54:57], v[200:215]
	v_cmp_lt_f32_e32 vcc, 8.0, v121
	s_cmp_eq_u32 s65, 0
	s_cbranch_scc1 .Ldsa_rf_fbe
	s_cbranch_vccnz .Ldsa_rare_fbe
.Ldsa_back_fbe:
	s_waitcnt lgkmcnt(0)
	v_lshrrev_b32_e32 v124, v148, v124
	v_mfma_f32_32x32x16_bf16 v[200:215], v[74:77], v[58:61], v[200:215]
	v_exp_f32_e32 v34, v34
	v_exp_f32_e32 v35, v35
	v_exp_f32_e32 v36, v36
	v_exp_f32_e32 v37, v37
	v_exp_f32_e32 v38, v38
	v_exp_f32_e32 v39, v39
	v_exp_f32_e32 v40, v40
	v_exp_f32_e32 v41, v41
	v_bfe_i32 v96, v124, 0, 1
	v_bfe_i32 v97, v124, 1, 1
	v_bfe_i32 v98, v124, 2, 1
	v_bfe_i32 v99, v124, 3, 1
	v_mfma_f32_32x32x16_bf16 v[200:215], v[78:81], v[62:65], v[200:215]
	v_bfe_i32 v100, v124, 4, 1
	v_bfe_i32 v101, v124, 5, 1
	v_bfe_i32 v102, v124, 6, 1
	v_bfe_i32 v103, v124, 7, 1
	v_and_b32_e32 v34, v96, v34
	v_and_b32_e32 v35, v97, v35
	v_and_b32_e32 v36, v98, v36
	v_and_b32_e32 v37, v99, v37
	v_and_b32_e32 v38, v100, v38
	v_and_b32_e32 v39, v101, v39
	v_and_b32_e32 v40, v102, v40
	v_and_b32_e32 v41, v103, v41
	v_add_f32_e32 v123, v34, v35
	v_add_f32_e32 v123, v123, v36
	v_add_f32_e32 v123, v123, v37
	v_add_f32_e32 v123, v123, v38
	v_add_f32_e32 v123, v123, v39
	v_add_f32_e32 v123, v123, v40
	v_add_f32_e32 v123, v123, v41
	v_cvt_pk_bf16_f32 v88, v34, v35
	v_cvt_pk_bf16_f32 v89, v36, v37
	v_cvt_pk_bf16_f32 v90, v38, v39
	v_cvt_pk_bf16_f32 v91, v40, v41
	v_exp_f32_e32 v42, v42
	v_exp_f32_e32 v43, v43
	v_mfma_f32_32x32x16_bf16 v[18:33], v[104:107], v[88:91], v[18:33]
	v_exp_f32_e32 v44, v44
	v_exp_f32_e32 v45, v45
	v_exp_f32_e32 v46, v46
	v_exp_f32_e32 v47, v47
	v_exp_f32_e32 v48, v48
	v_exp_f32_e32 v49, v49
	v_mfma_f32_32x32x16_bf16 v[2:17], v[108:111], v[88:91], v[2:17]
	v_bfe_i32 v96, v124, 16, 1
	v_bfe_i32 v97, v124, 17, 1
	v_bfe_i32 v98, v124, 18, 1
	v_bfe_i32 v99, v124, 19, 1
	v_bfe_i32 v100, v124, 20, 1
	v_bfe_i32 v101, v124, 21, 1
	v_bfe_i32 v102, v124, 22, 1
	v_bfe_i32 v103, v124, 23, 1
	v_and_b32_e32 v42, v96, v42
	v_and_b32_e32 v43, v97, v43
	v_and_b32_e32 v44, v98, v44
	v_and_b32_e32 v45, v99, v45
	v_and_b32_e32 v46, v100, v46
	v_and_b32_e32 v47, v101, v47
	v_and_b32_e32 v48, v102, v48
	v_and_b32_e32 v49, v103, v49
	v_add_f32_e32 v123, v123, v42
	v_add_f32_e32 v123, v123, v43
	v_add_f32_e32 v123, v123, v44
	v_add_f32_e32 v123, v123, v45
	v_add_f32_e32 v123, v123, v46
	v_add_f32_e32 v123, v123, v47
	v_add_f32_e32 v123, v123, v48
	v_add_f32_e32 v123, v123, v49
	v_cvt_pk_bf16_f32 v92, v42, v43
	v_cvt_pk_bf16_f32 v93, v44, v45
	v_cvt_pk_bf16_f32 v94, v46, v47
	v_cvt_pk_bf16_f32 v95, v48, v49
	v_add_f32_e32 v141, v141, v123
	s_nop 0
	v_mfma_f32_32x32x16_bf16 v[18:33], v[112:115], v[92:95], v[18:33]
	v_mfma_f32_32x32x16_bf16 v[2:17], v[116:119], v[92:95], v[2:17]
	s_branch .Ldsa_next_e

.Ldsa_fixret_lbe:
	v_add_u32_e32 v223, s40, v220
	v_add_u32_e32 v232, s40, v221
	ds_read_b128 v[104:107], v223 offset:4096
	ds_read_b128 v[108:111], v223 offset:6144
	ds_read_b128 v[112:115], v232 offset:4096
	ds_read_b128 v[116:119], v232 offset:6144
	v_add_u32_e32 v233, s66, v222
	ds_read_b32 v124, v233
	v_max3_f32 v121, v34, v35, v36
	v_max3_f32 v121, v121, v37, v38
	v_max3_f32 v121, v121, v39, v40
	v_max3_f32 v121, v121, v41, v42
	v_max3_f32 v121, v121, v43, v44
	v_max3_f32 v121, v121, v45, v46
	v_max3_f32 v121, v121, v47, v48
	v_max_f32_e32 v121, v121, v49
	v_mov_b32_e32 v122, v121
	s_nop 1
	v_permlane32_swap_b32_e32 v121, v122
	v_max_f32_e32 v121, v121, v122
	v_cmp_lt_f32_e32 vcc, 8.0, v121
	s_cmp_eq_u32 s65, 0
	s_cbranch_scc1 .Ldsa_rf_lbe
	s_cbranch_vccnz .Ldsa_rare_lbe
.Ldsa_back_lbe:
	s_waitcnt lgkmcnt(0)
	v_lshrrev_b32_e32 v124, v148, v124
	v_exp_f32_e32 v34, v34
	v_exp_f32_e32 v35, v35
	v_exp_f32_e32 v36, v36
	v_exp_f32_e32 v37, v37
	v_exp_f32_e32 v38, v38
	v_exp_f32_e32 v39, v39
	v_exp_f32_e32 v40, v40
	v_exp_f32_e32 v41, v41
	v_bfe_i32 v96, v124, 0, 1
	v_bfe_i32 v97, v124, 1, 1
	v_bfe_i32 v98, v124, 2, 1
	v_bfe_i32 v99, v124, 3, 1
	v_bfe_i32 v100, v124, 4, 1
	v_bfe_i32 v101, v124, 5, 1
	v_bfe_i32 v102, v124, 6, 1
	v_bfe_i32 v103, v124, 7, 1
	v_and_b32_e32 v34, v96, v34
	v_and_b32_e32 v35, v97, v35
	v_and_b32_e32 v36, v98, v36
	v_and_b32_e32 v37, v99, v37
	v_and_b32_e32 v38, v100, v38
	v_and_b32_e32 v39, v101, v39
	v_and_b32_e32 v40, v102, v40
	v_and_b32_e32 v41, v103, v41
	v_add_f32_e32 v123, v34, v35
	v_add_f32_e32 v123, v123, v36
	v_add_f32_e32 v123, v123, v37
	v_add_f32_e32 v123, v123, v38
	v_add_f32_e32 v123, v123, v39
	v_add_f32_e32 v123, v123, v40
	v_add_f32_e32 v123, v123, v41
	v_cvt_pk_bf16_f32 v88, v34, v35
	v_cvt_pk_bf16_f32 v89, v36, v37
	v_cvt_pk_bf16_f32 v90, v38, v39
	v_cvt_pk_bf16_f32 v91, v40, v41
	v_exp_f32_e32 v42, v42
	v_exp_f32_e32 v43, v43
	v_mfma_f32_32x32x16_bf16 v[18:33], v[104:107], v[88:91], v[18:33]
	v_exp_f32_e32 v44, v44
	v_exp_f32_e32 v45, v45
	v_exp_f32_e32 v46, v46
	v_exp_f32_e32 v47, v47
	v_exp_f32_e32 v48, v48
	v_exp_f32_e32 v49, v49
	v_mfma_f32_32x32x16_bf16 v[2:17], v[108:111], v[88:91], v[2:17]
	v_bfe_i32 v96, v124, 16, 1
	v_bfe_i32 v97, v124, 17, 1
	v_bfe_i32 v98, v124, 18, 1
	v_bfe_i32 v99, v124, 19, 1
	v_bfe_i32 v100, v124, 20, 1
	v_bfe_i32 v101, v124, 21, 1
	v_bfe_i32 v102, v124, 22, 1
	v_bfe_i32 v103, v124, 23, 1
	v_and_b32_e32 v42, v96, v42
	v_and_b32_e32 v43, v97, v43
	v_and_b32_e32 v44, v98, v44
	v_and_b32_e32 v45, v99, v45
	v_and_b32_e32 v46, v100, v46
	v_and_b32_e32 v47, v101, v47
	v_and_b32_e32 v48, v102, v48
	v_and_b32_e32 v49, v103, v49
	v_add_f32_e32 v123, v123, v42
	v_add_f32_e32 v123, v123, v43
	v_add_f32_e32 v123, v123, v44
	v_add_f32_e32 v123, v123, v45
	v_add_f32_e32 v123, v123, v46
	v_add_f32_e32 v123, v123, v47
	v_add_f32_e32 v123, v123, v48
	v_add_f32_e32 v123, v123, v49
	v_cvt_pk_bf16_f32 v92, v42, v43
	v_cvt_pk_bf16_f32 v93, v44, v45
	v_cvt_pk_bf16_f32 v94, v46, v47
	v_cvt_pk_bf16_f32 v95, v48, v49
	v_add_f32_e32 v141, v141, v123
	s_nop 0
	v_mfma_f32_32x32x16_bf16 v[18:33], v[112:115], v[92:95], v[18:33]
	v_mfma_f32_32x32x16_bf16 v[2:17], v[116:119], v[92:95], v[2:17]
	s_branch .Ldsa_next_e

.Ldsa_fixret_fbo:
	v_add_u32_e32 v128, s41, v216
	ds_read_b128 v[66:69], v128
	v_add_u32_e32 v129, s41, v217
	ds_read_b128 v[70:73], v129
	v_add_u32_e32 v173, s41, v218
	ds_read_b128 v[74:77], v173
	v_add_u32_e32 v175, s41, v219
	ds_read_b128 v[78:81], v175
	ds_read_b128 v[104:107], v223 offset:12288
	ds_read_b128 v[108:111], v223 offset:14336
	ds_read_b128 v[112:115], v232 offset:12288
	ds_read_b128 v[116:119], v232 offset:14336
	ds_read_b32 v124, v233 offset:4
	v_max3_f32 v121, v200, v201, v202
	v_max3_f32 v121, v121, v203, v204
	v_max3_f32 v121, v121, v205, v206
	v_max3_f32 v121, v121, v207, v208
	v_max3_f32 v121, v121, v209, v210
	v_max3_f32 v121, v121, v211, v212
	v_max3_f32 v121, v121, v213, v214
	v_max_f32_e32 v121, v121, v215
	s_waitcnt lgkmcnt(5)
	v_mfma_f32_32x32x16_bf16 v[34:49], v[66:69], v[50:53], v[178:193]
	v_mov_b32_e32 v122, v121
	s_nop 1
	v_permlane32_swap_b32_e32 v121, v122
	v_max_f32_e32 v121, v121, v122
	v_mfma_f32_32x32x16_bf16 v[34:49], v[70:73], v[54:57], v[34:49]
	v_cmp_lt_f32_e32 vcc, 8.0, v121
	s_cbranch_vccnz .Ldsa_rare_fbo
.Ldsa_back_fbo:
	s_waitcnt lgkmcnt(0)
	v_lshrrev_b32_e32 v124, v148, v124
	v_mfma_f32_32x32x16_bf16 v[34:49], v[74:77], v[58:61], v[34:49]
	v_exp_f32_e32 v200, v200
	v_exp_f32_e32 v201, v201
	v_exp_f32_e32 v202, v202
	v_exp_f32_e32 v203, v203
	v_exp_f32_e32 v204, v204
	v_exp_f32_e32 v205, v205
	v_exp_f32_e32 v206, v206
	v_exp_f32_e32 v207, v207
	v_bfe_i32 v96, v124, 0, 1
	v_bfe_i32 v97, v124, 1, 1
	v_bfe_i32 v98, v124, 2, 1
	v_bfe_i32 v99, v124, 3, 1
	v_mfma_f32_32x32x16_bf16 v[34:49], v[78:81], v[62:65], v[34:49]
	v_bfe_i32 v100, v124, 4, 1
	v_bfe_i32 v101, v124, 5, 1
	v_bfe_i32 v102, v124, 6, 1
	v_bfe_i32 v103, v124, 7, 1
	v_and_b32_e32 v200, v96, v200
	v_and_b32_e32 v201, v97, v201
	v_and_b32_e32 v202, v98, v202
	v_and_b32_e32 v203, v99, v203
	v_and_b32_e32 v204, v100, v204
	v_and_b32_e32 v205, v101, v205
	v_and_b32_e32 v206, v102, v206
	v_and_b32_e32 v207, v103, v207
	v_add_f32_e32 v123, v200, v201
	v_add_f32_e32 v123, v123, v202
	v_add_f32_e32 v123, v123, v203
	v_add_f32_e32 v123, v123, v204
	v_add_f32_e32 v123, v123, v205
	v_add_f32_e32 v123, v123, v206
	v_add_f32_e32 v123, v123, v207
	v_cvt_pk_bf16_f32 v88, v200, v201
	v_cvt_pk_bf16_f32 v89, v202, v203
	v_cvt_pk_bf16_f32 v90, v204, v205
	v_cvt_pk_bf16_f32 v91, v206, v207
	v_exp_f32_e32 v208, v208
	v_exp_f32_e32 v209, v209
	v_mfma_f32_32x32x16_bf16 v[18:33], v[104:107], v[88:91], v[18:33]
	v_exp_f32_e32 v210, v210
	v_exp_f32_e32 v211, v211
	v_exp_f32_e32 v212, v212
	v_exp_f32_e32 v213, v213
	v_exp_f32_e32 v214, v214
	v_exp_f32_e32 v215, v215
	v_mfma_f32_32x32x16_bf16 v[2:17], v[108:111], v[88:91], v[2:17]
	v_bfe_i32 v96, v124, 16, 1
	v_bfe_i32 v97, v124, 17, 1
	v_bfe_i32 v98, v124, 18, 1
	v_bfe_i32 v99, v124, 19, 1
	v_bfe_i32 v100, v124, 20, 1
	v_bfe_i32 v101, v124, 21, 1
	v_bfe_i32 v102, v124, 22, 1
	v_bfe_i32 v103, v124, 23, 1
	v_and_b32_e32 v208, v96, v208
	v_and_b32_e32 v209, v97, v209
	v_and_b32_e32 v210, v98, v210
	v_and_b32_e32 v211, v99, v211
	v_and_b32_e32 v212, v100, v212
	v_and_b32_e32 v213, v101, v213
	v_and_b32_e32 v214, v102, v214
	v_and_b32_e32 v215, v103, v215
	v_add_f32_e32 v123, v123, v208
	v_add_f32_e32 v123, v123, v209
	v_add_f32_e32 v123, v123, v210
	v_add_f32_e32 v123, v123, v211
	v_add_f32_e32 v123, v123, v212
	v_add_f32_e32 v123, v123, v213
	v_add_f32_e32 v123, v123, v214
	v_add_f32_e32 v123, v123, v215
	v_cvt_pk_bf16_f32 v92, v208, v209
	v_cvt_pk_bf16_f32 v93, v210, v211
	v_cvt_pk_bf16_f32 v94, v212, v213
	v_cvt_pk_bf16_f32 v95, v214, v215
	v_add_f32_e32 v141, v141, v123
	s_nop 0
	v_mfma_f32_32x32x16_bf16 v[18:33], v[112:115], v[92:95], v[18:33]
	v_mfma_f32_32x32x16_bf16 v[2:17], v[116:119], v[92:95], v[2:17]
	s_branch .Ldsa_next_o

.Ldsa_fixret_lbo:
	ds_read_b128 v[104:107], v223 offset:12288
	ds_read_b128 v[108:111], v223 offset:14336
	ds_read_b128 v[112:115], v232 offset:12288
	ds_read_b128 v[116:119], v232 offset:14336
	ds_read_b32 v124, v233 offset:4
	v_max3_f32 v121, v200, v201, v202
	v_max3_f32 v121, v121, v203, v204
	v_max3_f32 v121, v121, v205, v206
	v_max3_f32 v121, v121, v207, v208
	v_max3_f32 v121, v121, v209, v210
	v_max3_f32 v121, v121, v211, v212
	v_max3_f32 v121, v121, v213, v214
	v_max_f32_e32 v121, v121, v215
	v_mov_b32_e32 v122, v121
	s_nop 1
	v_permlane32_swap_b32_e32 v121, v122
	v_max_f32_e32 v121, v121, v122
	v_cmp_lt_f32_e32 vcc, 8.0, v121
	s_cbranch_vccnz .Ldsa_rare_lbo
.Ldsa_back_lbo:
	s_waitcnt lgkmcnt(0)
	v_lshrrev_b32_e32 v124, v148, v124
	v_exp_f32_e32 v200, v200
	v_exp_f32_e32 v201, v201
	v_exp_f32_e32 v202, v202
	v_exp_f32_e32 v203, v203
	v_exp_f32_e32 v204, v204
	v_exp_f32_e32 v205, v205
	v_exp_f32_e32 v206, v206
	v_exp_f32_e32 v207, v207
	v_bfe_i32 v96, v124, 0, 1
	v_bfe_i32 v97, v124, 1, 1
	v_bfe_i32 v98, v124, 2, 1
	v_bfe_i32 v99, v124, 3, 1
	v_bfe_i32 v100, v124, 4, 1
	v_bfe_i32 v101, v124, 5, 1
	v_bfe_i32 v102, v124, 6, 1
	v_bfe_i32 v103, v124, 7, 1
	v_and_b32_e32 v200, v96, v200
	v_and_b32_e32 v201, v97, v201
	v_and_b32_e32 v202, v98, v202
	v_and_b32_e32 v203, v99, v203
	v_and_b32_e32 v204, v100, v204
	v_and_b32_e32 v205, v101, v205
	v_and_b32_e32 v206, v102, v206
	v_and_b32_e32 v207, v103, v207
	v_add_f32_e32 v123, v200, v201
	v_add_f32_e32 v123, v123, v202
	v_add_f32_e32 v123, v123, v203
	v_add_f32_e32 v123, v123, v204
	v_add_f32_e32 v123, v123, v205
	v_add_f32_e32 v123, v123, v206
	v_add_f32_e32 v123, v123, v207
	v_cvt_pk_bf16_f32 v88, v200, v201
	v_cvt_pk_bf16_f32 v89, v202, v203
	v_cvt_pk_bf16_f32 v90, v204, v205
	v_cvt_pk_bf16_f32 v91, v206, v207
	v_exp_f32_e32 v208, v208
	v_exp_f32_e32 v209, v209
	v_mfma_f32_32x32x16_bf16 v[18:33], v[104:107], v[88:91], v[18:33]
	v_exp_f32_e32 v210, v210
	v_exp_f32_e32 v211, v211
	v_exp_f32_e32 v212, v212
	v_exp_f32_e32 v213, v213
	v_exp_f32_e32 v214, v214
	v_exp_f32_e32 v215, v215
	v_mfma_f32_32x32x16_bf16 v[2:17], v[108:111], v[88:91], v[2:17]
	v_bfe_i32 v96, v124, 16, 1
	v_bfe_i32 v97, v124, 17, 1
	v_bfe_i32 v98, v124, 18, 1
	v_bfe_i32 v99, v124, 19, 1
	v_bfe_i32 v100, v124, 20, 1
	v_bfe_i32 v101, v124, 21, 1
	v_bfe_i32 v102, v124, 22, 1
	v_bfe_i32 v103, v124, 23, 1
	v_and_b32_e32 v208, v96, v208
	v_and_b32_e32 v209, v97, v209
	v_and_b32_e32 v210, v98, v210
	v_and_b32_e32 v211, v99, v211
	v_and_b32_e32 v212, v100, v212
	v_and_b32_e32 v213, v101, v213
	v_and_b32_e32 v214, v102, v214
	v_and_b32_e32 v215, v103, v215
	v_add_f32_e32 v123, v123, v208
	v_add_f32_e32 v123, v123, v209
	v_add_f32_e32 v123, v123, v210
	v_add_f32_e32 v123, v123, v211
	v_add_f32_e32 v123, v123, v212
	v_add_f32_e32 v123, v123, v213
	v_add_f32_e32 v123, v123, v214
	v_add_f32_e32 v123, v123, v215
	v_cvt_pk_bf16_f32 v92, v208, v209
	v_cvt_pk_bf16_f32 v93, v210, v211
	v_cvt_pk_bf16_f32 v94, v212, v213
	v_cvt_pk_bf16_f32 v95, v214, v215
	v_add_f32_e32 v141, v141, v123
	s_nop 0
	v_mfma_f32_32x32x16_bf16 v[18:33], v[112:115], v[92:95], v[18:33]
	v_mfma_f32_32x32x16_bf16 v[2:17], v[116:119], v[92:95], v[2:17]
	s_branch .Ldsa_next_o

.Ldsa_rare_fbe:
	s_nop 15
	s_nop 15
	s_nop 15
	v_cndmask_b32_e32 v122, 0, v121, vcc
	v_add_f32_e32 v83, v83, v122
	v_exp_f32_e64 v126, -v122
	s_nop 0
	v_mul_f32_e32 v141, v141, v126
	v_pk_mul_f32 v[32:33], v[32:33], v[126:127] op_sel_hi:[1,0]
	v_pk_mul_f32 v[30:31], v[30:31], v[126:127] op_sel_hi:[1,0]
	v_pk_mul_f32 v[28:29], v[28:29], v[126:127] op_sel_hi:[1,0]
	v_pk_mul_f32 v[26:27], v[26:27], v[126:127] op_sel_hi:[1,0]
	v_pk_mul_f32 v[24:25], v[24:25], v[126:127] op_sel_hi:[1,0]
	v_pk_mul_f32 v[22:23], v[22:23], v[126:127] op_sel_hi:[1,0]
	v_pk_mul_f32 v[20:21], v[20:21], v[126:127] op_sel_hi:[1,0]
	v_pk_mul_f32 v[18:19], v[18:19], v[126:127] op_sel_hi:[1,0]
	v_pk_mul_f32 v[16:17], v[16:17], v[126:127] op_sel_hi:[1,0]
	v_pk_mul_f32 v[14:15], v[14:15], v[126:127] op_sel_hi:[1,0]
	v_pk_mul_f32 v[12:13], v[12:13], v[126:127] op_sel_hi:[1,0]
	v_pk_mul_f32 v[10:11], v[10:11], v[126:127] op_sel_hi:[1,0]
	v_pk_mul_f32 v[8:9], v[8:9], v[126:127] op_sel_hi:[1,0]
	v_pk_mul_f32 v[6:7], v[6:7], v[126:127] op_sel_hi:[1,0]
	v_pk_mul_f32 v[4:5], v[4:5], v[126:127] op_sel_hi:[1,0]
	v_pk_mul_f32 v[2:3], v[2:3], v[126:127] op_sel_hi:[1,0]
	v_sub_f32_e32 v34, v34, v122
	v_sub_f32_e32 v35, v35, v122
	v_sub_f32_e32 v36, v36, v122
	v_sub_f32_e32 v37, v37, v122
	v_sub_f32_e32 v38, v38, v122
	v_sub_f32_e32 v39, v39, v122
	v_sub_f32_e32 v40, v40, v122
	v_sub_f32_e32 v41, v41, v122
	v_sub_f32_e32 v42, v42, v122
	v_sub_f32_e32 v43, v43, v122
	v_sub_f32_e32 v44, v44, v122
	v_sub_f32_e32 v45, v45, v122
	v_sub_f32_e32 v46, v46, v122
	v_sub_f32_e32 v47, v47, v122
	v_sub_f32_e32 v48, v48, v122
	v_sub_f32_e32 v49, v49, v122
	v_sub_f32_e32 v178, v178, v122
	v_sub_f32_e32 v179, v179, v122
	v_sub_f32_e32 v180, v180, v122
	v_sub_f32_e32 v181, v181, v122
	v_sub_f32_e32 v182, v182, v122
	v_sub_f32_e32 v183, v183, v122
	v_sub_f32_e32 v184, v184, v122
	v_sub_f32_e32 v185, v185, v122
	v_sub_f32_e32 v186, v186, v122
	v_sub_f32_e32 v187, v187, v122
	v_sub_f32_e32 v188, v188, v122
	v_sub_f32_e32 v189, v189, v122
	v_sub_f32_e32 v190, v190, v122
	v_sub_f32_e32 v191, v191, v122
	v_sub_f32_e32 v192, v192, v122
	v_sub_f32_e32 v193, v193, v122
	v_mov_b32_e32 v234, v122
	s_mov_b32 s101, 1
	s_branch .Ldsa_back_fbe
.Ldsa_rf_fbe:
	s_nop 15
	s_nop 15
	s_nop 15
	v_mov_b32_e32 v122, v121
	v_mov_b32_e32 v83, v121
	v_sub_f32_e32 v34, v34, v122
	v_sub_f32_e32 v35, v35, v122
	v_sub_f32_e32 v36, v36, v122
	v_sub_f32_e32 v37, v37, v122
	v_sub_f32_e32 v38, v38, v122
	v_sub_f32_e32 v39, v39, v122
	v_sub_f32_e32 v40, v40, v122
	v_sub_f32_e32 v41, v41, v122
	v_sub_f32_e32 v42, v42, v122
	v_sub_f32_e32 v43, v43, v122
	v_sub_f32_e32 v44, v44, v122
	v_sub_f32_e32 v45, v45, v122
	v_sub_f32_e32 v46, v46, v122
	v_sub_f32_e32 v47, v47, v122
	v_sub_f32_e32 v48, v48, v122
	v_sub_f32_e32 v49, v49, v122
	v_sub_f32_e32 v178, v178, v122
	v_sub_f32_e32 v179, v179, v122
	v_sub_f32_e32 v180, v180, v122
	v_sub_f32_e32 v181, v181, v122
	v_sub_f32_e32 v182, v182, v122
	v_sub_f32_e32 v183, v183, v122
	v_sub_f32_e32 v184, v184, v122
	v_sub_f32_e32 v185, v185, v122
	v_sub_f32_e32 v186, v186, v122
	v_sub_f32_e32 v187, v187, v122
	v_sub_f32_e32 v188, v188, v122
	v_sub_f32_e32 v189, v189, v122
	v_sub_f32_e32 v190, v190, v122
	v_sub_f32_e32 v191, v191, v122
	v_sub_f32_e32 v192, v192, v122
	v_sub_f32_e32 v193, v193, v122
	v_mov_b32_e32 v234, v122
	s_mov_b32 s101, 1
	s_branch .Ldsa_back_fbe

.Ldsa_rare_fbo:
	s_nop 15
	s_nop 15
	s_nop 15
	v_cndmask_b32_e32 v122, 0, v121, vcc
	v_add_f32_e32 v83, v83, v122
	v_exp_f32_e64 v126, -v122
	s_nop 0
	v_mul_f32_e32 v141, v141, v126
	v_pk_mul_f32 v[32:33], v[32:33], v[126:127] op_sel_hi:[1,0]
	v_pk_mul_f32 v[30:31], v[30:31], v[126:127] op_sel_hi:[1,0]
	v_pk_mul_f32 v[28:29], v[28:29], v[126:127] op_sel_hi:[1,0]
	v_pk_mul_f32 v[26:27], v[26:27], v[126:127] op_sel_hi:[1,0]
	v_pk_mul_f32 v[24:25], v[24:25], v[126:127] op_sel_hi:[1,0]
	v_pk_mul_f32 v[22:23], v[22:23], v[126:127] op_sel_hi:[1,0]
	v_pk_mul_f32 v[20:21], v[20:21], v[126:127] op_sel_hi:[1,0]
	v_pk_mul_f32 v[18:19], v[18:19], v[126:127] op_sel_hi:[1,0]
	v_pk_mul_f32 v[16:17], v[16:17], v[126:127] op_sel_hi:[1,0]
	v_pk_mul_f32 v[14:15], v[14:15], v[126:127] op_sel_hi:[1,0]
	v_pk_mul_f32 v[12:13], v[12:13], v[126:127] op_sel_hi:[1,0]
	v_pk_mul_f32 v[10:11], v[10:11], v[126:127] op_sel_hi:[1,0]
	v_pk_mul_f32 v[8:9], v[8:9], v[126:127] op_sel_hi:[1,0]
	v_pk_mul_f32 v[6:7], v[6:7], v[126:127] op_sel_hi:[1,0]
	v_pk_mul_f32 v[4:5], v[4:5], v[126:127] op_sel_hi:[1,0]
	v_pk_mul_f32 v[2:3], v[2:3], v[126:127] op_sel_hi:[1,0]
	v_sub_f32_e32 v200, v200, v122
	v_sub_f32_e32 v201, v201, v122
	v_sub_f32_e32 v202, v202, v122
	v_sub_f32_e32 v203, v203, v122
	v_sub_f32_e32 v204, v204, v122
	v_sub_f32_e32 v205, v205, v122
	v_sub_f32_e32 v206, v206, v122
	v_sub_f32_e32 v207, v207, v122
	v_sub_f32_e32 v208, v208, v122
	v_sub_f32_e32 v209, v209, v122
	v_sub_f32_e32 v210, v210, v122
	v_sub_f32_e32 v211, v211, v122
	v_sub_f32_e32 v212, v212, v122
	v_sub_f32_e32 v213, v213, v122
	v_sub_f32_e32 v214, v214, v122
	v_sub_f32_e32 v215, v215, v122
	v_sub_f32_e32 v178, v178, v122
	v_sub_f32_e32 v179, v179, v122
	v_sub_f32_e32 v180, v180, v122
	v_sub_f32_e32 v181, v181, v122
	v_sub_f32_e32 v182, v182, v122
	v_sub_f32_e32 v183, v183, v122
	v_sub_f32_e32 v184, v184, v122
	v_sub_f32_e32 v185, v185, v122
	v_sub_f32_e32 v186, v186, v122
	v_sub_f32_e32 v187, v187, v122
	v_sub_f32_e32 v188, v188, v122
	v_sub_f32_e32 v189, v189, v122
	v_sub_f32_e32 v190, v190, v122
	v_sub_f32_e32 v191, v191, v122
	v_sub_f32_e32 v192, v192, v122
	v_sub_f32_e32 v193, v193, v122
	v_mov_b32_e32 v234, v122
	s_mov_b32 s101, 1
	s_branch .Ldsa_back_fbo

.Ldil_nok:
	s_nop 11
	v_max_f32_e32 v160, v113, v113
	v_max_f32_e32 v162, v112, v112
	v_max_f32_e32 v160, v162, v160
	v_max3_f32 v160, v160, v114, v115
	v_max3_f32 v160, v160, v116, v117
	v_max3_f32 v160, v160, v118, v119
	v_max3_f32 v160, v160, v120, v121
	v_max3_f32 v160, v160, v122, v123
	v_max3_f32 v160, v160, v124, v125
	v_max3_f32 v160, v160, v126, v127
	v_mov_b32_e32 v162, v160
	s_nop 1
	v_permlane32_swap_b32_e32 v160, v162
	v_max_f32_e32 v162, v162, v162
	v_max_f32_e32 v160, v160, v160
	v_max_f32_e32 v160, v160, v162
	v_add_f32_e32 v162, 0x41000000, v198
	v_cmp_gt_f32_e32 vcc, v160, v162
	s_cbranch_vccz .Ldil_soft
	s_nop 0
	v_cndmask_b32_e32 v162, v198, v160, vcc
	v_sub_f32_e32 v160, v198, v162
	v_mul_f32_e32 v160, 1.0, v160
	v_exp_f32_e32 v160, v160
	v_mov_b32_e32 v198, v162
	v_mul_f32_e32 v177, v177, v160
	v_pk_mul_f32 v[110:111], v[110:111], v[160:161] op_sel_hi:[1,0]
	v_pk_mul_f32 v[108:109], v[108:109], v[160:161] op_sel_hi:[1,0]
	v_pk_mul_f32 v[106:107], v[106:107], v[160:161] op_sel_hi:[1,0]
	v_pk_mul_f32 v[104:105], v[104:105], v[160:161] op_sel_hi:[1,0]
	v_pk_mul_f32 v[102:103], v[102:103], v[160:161] op_sel_hi:[1,0]
	v_pk_mul_f32 v[100:101], v[100:101], v[160:161] op_sel_hi:[1,0]
	v_pk_mul_f32 v[98:99], v[98:99], v[160:161] op_sel_hi:[1,0]
	v_pk_mul_f32 v[96:97], v[96:97], v[160:161] op_sel_hi:[1,0]
	v_pk_mul_f32 v[94:95], v[94:95], v[160:161] op_sel_hi:[1,0]
	v_pk_mul_f32 v[92:93], v[92:93], v[160:161] op_sel_hi:[1,0]
	v_pk_mul_f32 v[90:91], v[90:91], v[160:161] op_sel_hi:[1,0]
	v_pk_mul_f32 v[88:89], v[88:89], v[160:161] op_sel_hi:[1,0]
	v_pk_mul_f32 v[86:87], v[86:87], v[160:161] op_sel_hi:[1,0]
	v_pk_mul_f32 v[84:85], v[84:85], v[160:161] op_sel_hi:[1,0]
	v_pk_mul_f32 v[82:83], v[82:83], v[160:161] op_sel_hi:[1,0]
	v_pk_mul_f32 v[80:81], v[80:81], v[160:161] op_sel_hi:[1,0]
	v_pk_mul_f32 v[78:79], v[78:79], v[160:161] op_sel_hi:[1,0]
	v_pk_mul_f32 v[76:77], v[76:77], v[160:161] op_sel_hi:[1,0]
	v_pk_mul_f32 v[74:75], v[74:75], v[160:161] op_sel_hi:[1,0]
	v_pk_mul_f32 v[72:73], v[72:73], v[160:161] op_sel_hi:[1,0]
	v_pk_mul_f32 v[70:71], v[70:71], v[160:161] op_sel_hi:[1,0]
	v_pk_mul_f32 v[68:69], v[68:69], v[160:161] op_sel_hi:[1,0]
	v_pk_mul_f32 v[66:67], v[66:67], v[160:161] op_sel_hi:[1,0]
	v_pk_mul_f32 v[64:65], v[64:65], v[160:161] op_sel_hi:[1,0]
	v_pk_mul_f32 v[62:63], v[62:63], v[160:161] op_sel_hi:[1,0]
	v_pk_mul_f32 v[60:61], v[60:61], v[160:161] op_sel_hi:[1,0]
	v_pk_mul_f32 v[58:59], v[58:59], v[160:161] op_sel_hi:[1,0]
	v_pk_mul_f32 v[56:57], v[56:57], v[160:161] op_sel_hi:[1,0]
	v_pk_mul_f32 v[54:55], v[54:55], v[160:161] op_sel_hi:[1,0]
	v_pk_mul_f32 v[52:53], v[52:53], v[160:161] op_sel_hi:[1,0]
	v_pk_mul_f32 v[50:51], v[50:51], v[160:161] op_sel_hi:[1,0]
	v_pk_mul_f32 v[48:49], v[48:49], v[160:161] op_sel_hi:[1,0]
	v_pk_mul_f32 v[46:47], v[46:47], v[160:161] op_sel_hi:[1,0]
	v_pk_mul_f32 v[44:45], v[44:45], v[160:161] op_sel_hi:[1,0]
	v_pk_mul_f32 v[42:43], v[42:43], v[160:161] op_sel_hi:[1,0]
	v_pk_mul_f32 v[40:41], v[40:41], v[160:161] op_sel_hi:[1,0]
	v_pk_mul_f32 v[38:39], v[38:39], v[160:161] op_sel_hi:[1,0]
	v_pk_mul_f32 v[36:37], v[36:37], v[160:161] op_sel_hi:[1,0]
	v_pk_mul_f32 v[34:35], v[34:35], v[160:161] op_sel_hi:[1,0]
	v_pk_mul_f32 v[32:33], v[32:33], v[160:161] op_sel_hi:[1,0]
	v_pk_mul_f32 v[30:31], v[30:31], v[160:161] op_sel_hi:[1,0]
	v_pk_mul_f32 v[28:29], v[28:29], v[160:161] op_sel_hi:[1,0]
	v_pk_mul_f32 v[26:27], v[26:27], v[160:161] op_sel_hi:[1,0]
	v_pk_mul_f32 v[24:25], v[24:25], v[160:161] op_sel_hi:[1,0]
	v_pk_mul_f32 v[22:23], v[22:23], v[160:161] op_sel_hi:[1,0]
	v_pk_mul_f32 v[20:21], v[20:21], v[160:161] op_sel_hi:[1,0]
	v_pk_mul_f32 v[18:19], v[18:19], v[160:161] op_sel_hi:[1,0]
	v_pk_mul_f32 v[16:17], v[16:17], v[160:161] op_sel_hi:[1,0]
.Ldil_soft:
	v_mul_f32_e32 v160, -1.0, v198
	v_fmamk_f32 v112, v112, 1.0, v160
	v_exp_f32_e32 v112, v112
	v_fmamk_f32 v113, v113, 1.0, v160
	v_exp_f32_e32 v113, v113
	v_fmamk_f32 v114, v114, 1.0, v160
	v_exp_f32_e32 v114, v114
	v_fmamk_f32 v115, v115, 1.0, v160
	v_cmp_gt_u32_e32 vcc, s75, v0
	v_add_u32_e32 v163, -1, v0
	v_exp_f32_e32 v115, v115
	v_fmamk_f32 v116, v116, 1.0, v160
	v_cndmask_b32_e32 v112, 0, v112, vcc
	v_cmp_gt_u32_e32 vcc, s75, v163
	v_add_u32_e32 v163, -2, v0
	v_exp_f32_e32 v116, v116
	v_fmamk_f32 v117, v117, 1.0, v160
	v_add_f32_e32 v162, 0, v112
	v_cndmask_b32_e32 v113, 0, v113, vcc
	v_cmp_gt_u32_e32 vcc, s75, v163
	v_add_u32_e32 v163, -3, v0
	v_exp_f32_e32 v117, v117
	v_fmamk_f32 v118, v118, 1.0, v160
	v_add_f32_e32 v162, v113, v162
	v_cndmask_b32_e32 v114, 0, v114, vcc
	v_cmp_gt_u32_e32 vcc, s75, v163
	v_add_u32_e32 v163, -4, v0
	v_exp_f32_e32 v118, v118
	v_fmamk_f32 v119, v119, 1.0, v160
	v_add_f32_e32 v162, v114, v162
	v_cndmask_b32_e32 v115, 0, v115, vcc
	v_cmp_gt_u32_e32 vcc, s75, v163
	v_add_u32_e32 v163, -5, v0
	v_exp_f32_e32 v119, v119
	v_fmamk_f32 v120, v120, 1.0, v160
	v_add_f32_e32 v162, v115, v162
	v_cndmask_b32_e32 v116, 0, v116, vcc
	v_cmp_gt_u32_e32 vcc, s75, v163
	v_add_u32_e32 v163, -6, v0
	v_exp_f32_e32 v120, v120
	v_fmamk_f32 v121, v121, 1.0, v160
	v_add_f32_e32 v162, v116, v162
	v_cndmask_b32_e32 v117, 0, v117, vcc
	v_cmp_gt_u32_e32 vcc, s75, v163
	v_add_u32_e32 v163, -7, v0
	v_exp_f32_e32 v121, v121
	v_fmamk_f32 v122, v122, 1.0, v160
	v_add_f32_e32 v162, v117, v162
	v_cndmask_b32_e32 v118, 0, v118, vcc
	v_cmp_gt_u32_e32 vcc, s75, v163
	v_add_u32_e32 v163, -16, v0
	v_exp_f32_e32 v122, v122
	v_fmamk_f32 v123, v123, 1.0, v160
	v_add_f32_e32 v162, v118, v162
	v_cndmask_b32_e32 v119, 0, v119, vcc
	v_cmp_gt_u32_e32 vcc, s75, v163
	v_subrev_u32_e32 v163, 17, v0
	v_exp_f32_e32 v123, v123
	v_fmamk_f32 v124, v124, 1.0, v160
	v_add_f32_e32 v162, v119, v162
	v_cndmask_b32_e32 v120, 0, v120, vcc
	v_cmp_gt_u32_e32 vcc, s75, v163
	v_subrev_u32_e32 v163, 18, v0
	v_exp_f32_e32 v124, v124
	v_fmamk_f32 v125, v125, 1.0, v160
	v_add_f32_e32 v162, v120, v162
	v_cndmask_b32_e32 v121, 0, v121, vcc
	v_cmp_gt_u32_e32 vcc, s75, v163
	v_subrev_u32_e32 v163, 19, v0
	v_exp_f32_e32 v125, v125
	v_fmamk_f32 v126, v126, 1.0, v160
	v_add_f32_e32 v162, v121, v162
	v_cndmask_b32_e32 v122, 0, v122, vcc
	v_cmp_gt_u32_e32 vcc, s75, v163
	v_subrev_u32_e32 v163, 20, v0
	v_exp_f32_e32 v126, v126
	v_fmac_f32_e32 v160, 1.0, v127
	v_add_f32_e32 v162, v122, v162
	v_cndmask_b32_e32 v123, 0, v123, vcc
	v_cmp_gt_u32_e32 vcc, s75, v163
	v_subrev_u32_e32 v163, 21, v0
	v_exp_f32_e32 v127, v160
	v_add_f32_e32 v162, v123, v162
	v_cndmask_b32_e32 v124, 0, v124, vcc
	v_cmp_gt_u32_e32 vcc, s75, v163
	v_subrev_u32_e32 v163, 22, v0
	v_add_f32_e32 v162, v124, v162
	v_cndmask_b32_e32 v125, 0, v125, vcc
	v_cmp_gt_u32_e32 vcc, s75, v163
	v_subrev_u32_e32 v160, 23, v0
	v_add_f32_e32 v162, v125, v162
	v_cndmask_b32_e32 v126, 0, v126, vcc
	v_cmp_gt_u32_e32 vcc, s75, v160
	v_add_f32_e32 v162, v126, v162
	v_cndmask_b32_e32 v127, 0, v127, vcc
	v_add_f32_e32 v160, v127, v162
	v_add_f32_e32 v177, v177, v160
	v_cvt_pk_bf16_f32 v112, v112, v113
	v_cvt_pk_bf16_f32 v113, v114, v115
	v_cvt_pk_bf16_f32 v114, v116, v117
	v_cvt_pk_bf16_f32 v115, v118, v119
	v_cvt_pk_bf16_f32 v116, v120, v121
	v_cvt_pk_bf16_f32 v118, v124, v125
	v_cvt_pk_bf16_f32 v117, v122, v123
	v_cvt_pk_bf16_f32 v119, v126, v127
	s_cmp_lt_i32 s44, s43
	s_cbranch_scc0 .Ldil_w0
	s_waitcnt vmcnt(4)
	s_branch .Ldil_pv

.Ldil_g0ni:
	v_add_u32_e32 v203, s46, v199
	ds_read_b128 v[132:135], v203 offset:12288
	ds_read_b128 v[136:139], v203 offset:13312
	ds_read_b128 v[140:143], v203 offset:14336
	ds_read_b128 v[144:147], v203 offset:15360
	ds_read_b128 v[214:217], v203
	ds_read_b128 v[218:221], v203 offset:1024
	ds_read_b128 v[222:225], v203 offset:2048
	ds_read_b128 v[226:229], v203 offset:3072
	ds_read_b128 v[230:233], v203 offset:4096
	ds_read_b128 v[244:247], v203 offset:5120
	ds_read_b128 v[248:251], v203 offset:6144
	ds_read_b128 v[164:167], v203 offset:7168
	ds_read_b128 v[148:151], v203 offset:8192
	ds_read_b128 v[152:155], v203 offset:9216
	ds_read_b128 v[156:159], v203 offset:10240
	ds_read_b128 v[200:203], v203 offset:11264
	s_add_i32 s46, s46, 0x4000
	s_cmp_eq_u32 s46, 0x14000
	s_cselect_b32 s46, 0, s46
	s_waitcnt lgkmcnt(12)
	v_mfma_f32_32x32x16_bf16 v[112:127], v[132:135], v[2:5], 0
	v_mfma_f32_32x32x16_bf16 v[112:127], v[136:139], v[6:9], v[112:127]
	v_mfma_f32_32x32x16_bf16 v[112:127], v[140:143], v[10:13], v[112:127]
	v_mfma_f32_32x32x16_bf16 v[112:127], v[144:147], v[128:131], v[112:127]
	s_add_i32 s44, s44, 1
	s_nop 11
	v_max_f32_e32 v160, v113, v113
	v_max_f32_e32 v162, v112, v112
	v_max_f32_e32 v160, v162, v160
	v_max3_f32 v160, v160, v114, v115
	v_max3_f32 v160, v160, v116, v117
	v_max3_f32 v160, v160, v118, v119
	v_max3_f32 v160, v160, v120, v121
	v_max3_f32 v160, v160, v122, v123
	v_max3_f32 v160, v160, v124, v125
	v_max3_f32 v160, v160, v126, v127
	v_mov_b32_e32 v162, v160
	s_nop 1
	v_permlane32_swap_b32_e32 v160, v162
	v_max_f32_e32 v162, v162, v162
	v_max_f32_e32 v160, v160, v160
	v_max_f32_e32 v160, v160, v162
	v_add_f32_e32 v162, 0x41000000, v198
	v_cmp_gt_f32_e32 vcc, v160, v162
	s_cbranch_vccz .Ldil_g0soft
	s_nop 0
	v_cndmask_b32_e32 v162, v198, v160, vcc
	v_sub_f32_e32 v160, v198, v162
	v_mul_f32_e32 v160, 1.0, v160
	v_exp_f32_e32 v160, v160
	v_mov_b32_e32 v198, v162
	v_mul_f32_e32 v177, v177, v160
	v_pk_mul_f32 v[110:111], v[110:111], v[160:161] op_sel_hi:[1,0]
	v_pk_mul_f32 v[108:109], v[108:109], v[160:161] op_sel_hi:[1,0]
	v_pk_mul_f32 v[106:107], v[106:107], v[160:161] op_sel_hi:[1,0]
	v_pk_mul_f32 v[104:105], v[104:105], v[160:161] op_sel_hi:[1,0]
	v_pk_mul_f32 v[102:103], v[102:103], v[160:161] op_sel_hi:[1,0]
	v_pk_mul_f32 v[100:101], v[100:101], v[160:161] op_sel_hi:[1,0]
	v_pk_mul_f32 v[98:99], v[98:99], v[160:161] op_sel_hi:[1,0]
	v_pk_mul_f32 v[96:97], v[96:97], v[160:161] op_sel_hi:[1,0]
	v_pk_mul_f32 v[94:95], v[94:95], v[160:161] op_sel_hi:[1,0]
	v_pk_mul_f32 v[92:93], v[92:93], v[160:161] op_sel_hi:[1,0]
	v_pk_mul_f32 v[90:91], v[90:91], v[160:161] op_sel_hi:[1,0]
	v_pk_mul_f32 v[88:89], v[88:89], v[160:161] op_sel_hi:[1,0]
	v_pk_mul_f32 v[86:87], v[86:87], v[160:161] op_sel_hi:[1,0]
	v_pk_mul_f32 v[84:85], v[84:85], v[160:161] op_sel_hi:[1,0]
	v_pk_mul_f32 v[82:83], v[82:83], v[160:161] op_sel_hi:[1,0]
	v_pk_mul_f32 v[80:81], v[80:81], v[160:161] op_sel_hi:[1,0]
	v_pk_mul_f32 v[78:79], v[78:79], v[160:161] op_sel_hi:[1,0]
	v_pk_mul_f32 v[76:77], v[76:77], v[160:161] op_sel_hi:[1,0]
	v_pk_mul_f32 v[74:75], v[74:75], v[160:161] op_sel_hi:[1,0]
	v_pk_mul_f32 v[72:73], v[72:73], v[160:161] op_sel_hi:[1,0]
	v_pk_mul_f32 v[70:71], v[70:71], v[160:161] op_sel_hi:[1,0]
	v_pk_mul_f32 v[68:69], v[68:69], v[160:161] op_sel_hi:[1,0]
	v_pk_mul_f32 v[66:67], v[66:67], v[160:161] op_sel_hi:[1,0]
	v_pk_mul_f32 v[64:65], v[64:65], v[160:161] op_sel_hi:[1,0]
	v_pk_mul_f32 v[62:63], v[62:63], v[160:161] op_sel_hi:[1,0]
	v_pk_mul_f32 v[60:61], v[60:61], v[160:161] op_sel_hi:[1,0]
	v_pk_mul_f32 v[58:59], v[58:59], v[160:161] op_sel_hi:[1,0]
	v_pk_mul_f32 v[56:57], v[56:57], v[160:161] op_sel_hi:[1,0]
	v_pk_mul_f32 v[54:55], v[54:55], v[160:161] op_sel_hi:[1,0]
	v_pk_mul_f32 v[52:53], v[52:53], v[160:161] op_sel_hi:[1,0]
	v_pk_mul_f32 v[50:51], v[50:51], v[160:161] op_sel_hi:[1,0]
	v_pk_mul_f32 v[48:49], v[48:49], v[160:161] op_sel_hi:[1,0]
	v_pk_mul_f32 v[46:47], v[46:47], v[160:161] op_sel_hi:[1,0]
	v_pk_mul_f32 v[44:45], v[44:45], v[160:161] op_sel_hi:[1,0]
	v_pk_mul_f32 v[42:43], v[42:43], v[160:161] op_sel_hi:[1,0]
	v_pk_mul_f32 v[40:41], v[40:41], v[160:161] op_sel_hi:[1,0]
	v_pk_mul_f32 v[38:39], v[38:39], v[160:161] op_sel_hi:[1,0]
	v_pk_mul_f32 v[36:37], v[36:37], v[160:161] op_sel_hi:[1,0]
	v_pk_mul_f32 v[34:35], v[34:35], v[160:161] op_sel_hi:[1,0]
	v_pk_mul_f32 v[32:33], v[32:33], v[160:161] op_sel_hi:[1,0]
	v_pk_mul_f32 v[30:31], v[30:31], v[160:161] op_sel_hi:[1,0]
	v_pk_mul_f32 v[28:29], v[28:29], v[160:161] op_sel_hi:[1,0]
	v_pk_mul_f32 v[26:27], v[26:27], v[160:161] op_sel_hi:[1,0]
	v_pk_mul_f32 v[24:25], v[24:25], v[160:161] op_sel_hi:[1,0]
	v_pk_mul_f32 v[22:23], v[22:23], v[160:161] op_sel_hi:[1,0]
	v_pk_mul_f32 v[20:21], v[20:21], v[160:161] op_sel_hi:[1,0]
	v_pk_mul_f32 v[18:19], v[18:19], v[160:161] op_sel_hi:[1,0]
	v_pk_mul_f32 v[16:17], v[16:17], v[160:161] op_sel_hi:[1,0]
.Ldil_g0soft:
	v_mul_f32_e32 v160, -1.0, v198
	v_fmamk_f32 v112, v112, 1.0, v160
	v_exp_f32_e32 v112, v112
	v_fmamk_f32 v113, v113, 1.0, v160
	v_exp_f32_e32 v113, v113
	v_fmamk_f32 v114, v114, 1.0, v160
	v_exp_f32_e32 v114, v114
	v_fmamk_f32 v115, v115, 1.0, v160
	v_cmp_gt_u32_e32 vcc, s75, v0
	v_add_u32_e32 v163, -1, v0
	v_exp_f32_e32 v115, v115
	v_fmamk_f32 v116, v116, 1.0, v160
	v_cndmask_b32_e32 v112, 0, v112, vcc
	v_cmp_gt_u32_e32 vcc, s75, v163
	v_add_u32_e32 v163, -2, v0
	v_exp_f32_e32 v116, v116
	v_fmamk_f32 v117, v117, 1.0, v160
	v_add_f32_e32 v162, 0, v112
	v_cndmask_b32_e32 v113, 0, v113, vcc
	v_cmp_gt_u32_e32 vcc, s75, v163
	v_add_u32_e32 v163, -3, v0
	v_exp_f32_e32 v117, v117
	v_fmamk_f32 v118, v118, 1.0, v160
	v_add_f32_e32 v162, v113, v162
	v_cndmask_b32_e32 v114, 0, v114, vcc
	v_cmp_gt_u32_e32 vcc, s75, v163
	v_add_u32_e32 v163, -4, v0
	v_exp_f32_e32 v118, v118
	v_fmamk_f32 v119, v119, 1.0, v160
	v_add_f32_e32 v162, v114, v162
	v_cndmask_b32_e32 v115, 0, v115, vcc
	v_cmp_gt_u32_e32 vcc, s75, v163
	v_add_u32_e32 v163, -5, v0
	v_exp_f32_e32 v119, v119
	v_fmamk_f32 v120, v120, 1.0, v160
	v_add_f32_e32 v162, v115, v162
	v_cndmask_b32_e32 v116, 0, v116, vcc
	v_cmp_gt_u32_e32 vcc, s75, v163
	v_add_u32_e32 v163, -6, v0
	v_exp_f32_e32 v120, v120
	v_fmamk_f32 v121, v121, 1.0, v160
	v_add_f32_e32 v162, v116, v162
	v_cndmask_b32_e32 v117, 0, v117, vcc
	v_cmp_gt_u32_e32 vcc, s75, v163
	v_add_u32_e32 v163, -7, v0
	v_exp_f32_e32 v121, v121
	v_fmamk_f32 v122, v122, 1.0, v160
	v_add_f32_e32 v162, v117, v162
	v_cndmask_b32_e32 v118, 0, v118, vcc
	v_cmp_gt_u32_e32 vcc, s75, v163
	v_add_u32_e32 v163, -16, v0
	v_exp_f32_e32 v122, v122
	v_fmamk_f32 v123, v123, 1.0, v160
	v_add_f32_e32 v162, v118, v162
	v_cndmask_b32_e32 v119, 0, v119, vcc
	v_cmp_gt_u32_e32 vcc, s75, v163
	v_subrev_u32_e32 v163, 17, v0
	v_exp_f32_e32 v123, v123
	v_fmamk_f32 v124, v124, 1.0, v160
	v_add_f32_e32 v162, v119, v162
	v_cndmask_b32_e32 v120, 0, v120, vcc
	v_cmp_gt_u32_e32 vcc, s75, v163
	v_subrev_u32_e32 v163, 18, v0
	v_exp_f32_e32 v124, v124
	v_fmamk_f32 v125, v125, 1.0, v160
	v_add_f32_e32 v162, v120, v162
	v_cndmask_b32_e32 v121, 0, v121, vcc
	v_cmp_gt_u32_e32 vcc, s75, v163
	v_subrev_u32_e32 v163, 19, v0
	v_exp_f32_e32 v125, v125
	v_fmamk_f32 v126, v126, 1.0, v160
	v_add_f32_e32 v162, v121, v162
	v_cndmask_b32_e32 v122, 0, v122, vcc
	v_cmp_gt_u32_e32 vcc, s75, v163
	v_subrev_u32_e32 v163, 20, v0
	v_exp_f32_e32 v126, v126
	v_fmac_f32_e32 v160, 1.0, v127
	v_add_f32_e32 v162, v122, v162
	v_cndmask_b32_e32 v123, 0, v123, vcc
	v_cmp_gt_u32_e32 vcc, s75, v163
	v_subrev_u32_e32 v163, 21, v0
	v_exp_f32_e32 v127, v160
	v_add_f32_e32 v162, v123, v162
	v_cndmask_b32_e32 v124, 0, v124, vcc
	v_cmp_gt_u32_e32 vcc, s75, v163
	v_subrev_u32_e32 v163, 22, v0
	v_add_f32_e32 v162, v124, v162
	v_cndmask_b32_e32 v125, 0, v125, vcc
	v_cmp_gt_u32_e32 vcc, s75, v163
	v_subrev_u32_e32 v160, 23, v0
	v_add_f32_e32 v162, v125, v162
	v_cndmask_b32_e32 v126, 0, v126, vcc
	v_cmp_gt_u32_e32 vcc, s75, v160
	v_add_f32_e32 v162, v126, v162
	v_cndmask_b32_e32 v127, 0, v127, vcc
	v_add_f32_e32 v160, v127, v162
	v_add_f32_e32 v177, v177, v160
	v_cvt_pk_bf16_f32 v112, v112, v113
	v_cvt_pk_bf16_f32 v113, v114, v115
	v_cvt_pk_bf16_f32 v114, v116, v117
	v_cvt_pk_bf16_f32 v115, v118, v119
	v_cvt_pk_bf16_f32 v116, v120, v121
	v_cvt_pk_bf16_f32 v118, v124, v125
	v_cvt_pk_bf16_f32 v117, v122, v123
	v_cvt_pk_bf16_f32 v119, v126, v127
	s_waitcnt lgkmcnt(0)
	s_nop 0
	v_mfma_f32_32x32x16_bf16 v[96:111], v[214:217], v[112:115], v[96:111]
	v_mfma_f32_32x32x16_bf16 v[80:95], v[222:225], v[112:115], v[80:95]
	v_mfma_f32_32x32x16_bf16 v[64:79], v[230:233], v[112:115], v[64:79]
	v_mfma_f32_32x32x16_bf16 v[48:63], v[248:251], v[112:115], v[48:63]
	v_mfma_f32_32x32x16_bf16 v[32:47], v[148:151], v[112:115], v[32:47]
	v_mfma_f32_32x32x16_bf16 v[16:31], v[156:159], v[112:115], v[16:31]
	v_mfma_f32_32x32x16_bf16 v[96:111], v[218:221], v[116:119], v[96:111]
	v_mfma_f32_32x32x16_bf16 v[80:95], v[226:229], v[116:119], v[80:95]
	v_mfma_f32_32x32x16_bf16 v[64:79], v[244:247], v[116:119], v[64:79]
	v_mfma_f32_32x32x16_bf16 v[48:63], v[164:167], v[116:119], v[48:63]
	v_mfma_f32_32x32x16_bf16 v[32:47], v[152:155], v[116:119], v[32:47]
	v_mfma_f32_32x32x16_bf16 v[16:31], v[200:203], v[116:119], v[16:31]
	v_subrev_u32_e32 v0, 32, v0
	s_cmp_lt_i32 s44, s43
	s_cbranch_scc1 .Ldil_g0top
